# GEMM K loops of phases 1 and 10: hipcc's per-phase s_setprio flips removed, one static priority raise for waves 4-7 for the whole phase (reset at phase exit); on v079
# speedup vs baseline: 1.0095x; 1.0091x over previous
.LBB0_173:
	s_and_b32 s3, s0, 3
	s_mov_b64 s[0:1], 0x80
	s_add_i32 m0, s58, 0x18000
	v_lshl_add_u64 v[6:7], v[6:7], 0, s[0:1]
	s_ashr_i32 s63, s90, 31
	s_ashr_i32 s64, s16, 31
	s_lshl_b32 s6, s2, 13
	s_lshl_b32 s7, s3, 12
	s_waitcnt vmcnt(4)
	s_barrier
	global_load_lds_dwordx4 v[6:7], off
	v_lshl_add_u64 v[4:5], v[4:5], 0, s[0:1]
	s_add_i32 m0, s58, 0x1a000
	s_add_i32 s65, s58, 0x8000
	s_add_i32 s66, s58, 0xa000
	global_load_lds_dwordx4 v[4:5], off
	v_lshl_add_u64 v[2:3], v[2:3], 0, s[0:1]
	s_mov_b32 m0, s65
	s_add_u32 s4, s52, 0x10080
	global_load_lds_dwordx4 v[2:3], off
	v_lshl_add_u64 v[0:1], v[0:1], 0, s[0:1]
	s_mov_b32 m0, s66
	s_addc_u32 s5, s53, 0
	global_load_lds_dwordx4 v[0:1], off
	s_add_i32 m0, s58, 0x1c000
	v_lshl_add_u64 v[0:1], s[4:5], 0, v[130:131]
	global_load_lds_dwordx4 v[0:1], off
	v_lshl_add_u64 v[0:1], s[4:5], 0, v[134:135]
	s_add_i32 m0, s58, 0x1e000
	v_lshlrev_b32_e32 v3, 2, v8
	global_load_lds_dwordx4 v[0:1], off
	v_bfe_u32 v1, v8, 4, 2
	v_and_b32_e32 v0, 15, v8
	v_lshlrev_b32_e32 v2, 4, v1
	v_lshl_or_b32 v2, v0, 6, v2
	v_and_b32_e32 v3, 32, v3
	v_bitop3_b32 v4, v2, s6, v3 bitop3:0xde
	v_bitop3_b32 v158, v2, s7, v3 bitop3:0xde
	v_cmp_gt_u32_e64 s[6:7], 8, v0
	v_lshl_or_b32 v139, s2, 6, v0
	s_lshl_b32 s87, s3, 6
	v_cndmask_b32_e64 v0, 32, 0, s[6:7]
	v_lshl_or_b32 v138, v1, 3, v0
	v_lshlrev_b32_e32 v0, 14, v9
	v_and_b32_e32 v0, 0xffff8000, v0
	v_cmp_gt_u32_e64 s[2:3], 2, v1
	v_cmp_eq_u32_e64 s[4:5], 0, v1
	v_lshl_add_u32 v0, v10, 11, v0
	v_and_b32_e32 v1, 1, v9
	v_lshl_or_b32 v0, v1, 6, v0
	v_lshl_add_u32 v140, v11, 1, v0
	v_lshlrev_b32_e32 v0, 14, v12
	v_and_b32_e32 v0, 0xffff8000, v0
	v_lshl_add_u32 v0, v13, 11, v0
	v_and_b32_e32 v1, 1, v12
	s_waitcnt vmcnt(6)
	v_lshl_or_b32 v0, v1, 6, v0
	s_mov_b64 s[28:29], s[90:91]
	s_mov_b32 s67, s90
	v_lshl_add_u32 v142, v14, 1, v0
	s_add_i32 s89, 0, 0x10000
	s_add_i32 s90, 0, 0x14000
	s_movk_i32 s40, 0xe800
	v_mbcnt_lo_u32_b32 v0, -1, 0
	v_mov_b32_e32 v141, v137
	v_mov_b32_e32 v143, v137
	v_mov_b64_e32 v[144:145], 0xa00
	v_mov_b64_e32 v[146:147], 0x9ff
	s_movk_i32 s88, 0x141
	v_add_u32_e32 v159, s89, v158
	v_add_u32_e32 v160, 0, v4
	v_add_u32_e32 v161, s90, v158
	s_mov_b32 s41, -1
	v_mbcnt_hi_u32_b32 v162, -1, v0
	s_barrier
	s_mov_b32 s98, 0
	s_cmpk_gt_u32 s56, 0xff
	s_cbranch_scc0 .Lpr_lbb0_178
	s_setprio 1
.Lpr_lbb0_178:
	s_branch .LBB0_175
.LBB0_174:
	s_mov_b32 s98, 1
	s_and_b64 vcc, exec, s[8:9]
	s_mov_b32 s10, s42
	s_mov_b32 s12, s44
	s_mov_b64 s[52:53], s[48:49]
	s_mov_b64 s[50:51], s[46:47]
	s_cbranch_vccnz .LBB0_275

.LBB0_178:
	ds_read_b128 v[148:151], v159
	ds_read_b128 v[152:155], v159 offset:1024
	ds_read_b128 v[164:167], v159 offset:2048
	ds_read_b128 v[168:171], v159 offset:3072
	s_add_u32 s52, s50, 0xfffc0080
	s_addc_u32 s53, s51, -1
	s_cmp_eq_u32 s92, 12
	s_cselect_b32 s55, s11, s53
	s_cselect_b32 s54, s13, s52
	s_cselect_b32 s53, s17, s91
	s_cselect_b32 s52, s43, s45
	v_lshl_add_u64 v[156:157], s[50:51], 0, v[140:141]
	s_add_i32 m0, s58, 0xc000
	ds_read_b128 v[172:175], v160
	ds_read_b128 v[176:179], v160 offset:1024
	ds_read_b128 v[180:183], v160 offset:2048
	ds_read_b128 v[184:187], v160 offset:3072
	ds_read_b128 v[188:191], v160 offset:4096
	ds_read_b128 v[196:199], v160 offset:5120
	ds_read_b128 v[200:203], v160 offset:6144
	ds_read_b128 v[204:207], v160 offset:7168
	global_load_lds_dwordx4 v[156:157], off
	v_lshl_add_u64 v[156:157], s[50:51], 0, v[142:143]
	s_add_i32 m0, s58, 0xe000
	s_nop 0
	global_load_lds_dwordx4 v[156:157], off
	s_waitcnt lgkmcnt(8)
	s_barrier
	s_waitcnt lgkmcnt(0)
	s_waitcnt lgkmcnt(0)
	s_cmp_eq_u32 s92, -2
	s_cbranch_scc1 .Lz1_0_first
	v_mfma_f32_16x16x32_bf16 v[124:127], v[148:151], v[172:175], v[124:127]
	v_mfma_f32_16x16x32_bf16 v[120:123], v[164:167], v[172:175], v[120:123]
	v_mfma_f32_16x16x32_bf16 v[108:111], v[148:151], v[180:183], v[108:111]
	v_mfma_f32_16x16x32_bf16 v[104:107], v[164:167], v[180:183], v[104:107]
	v_mfma_f32_16x16x32_bf16 v[92:95], v[148:151], v[188:191], v[92:95]
	v_mfma_f32_16x16x32_bf16 v[88:91], v[164:167], v[188:191], v[88:91]
	v_mfma_f32_16x16x32_bf16 v[76:79], v[148:151], v[200:203], v[76:79]
	v_mfma_f32_16x16x32_bf16 v[72:75], v[164:167], v[200:203], v[72:75]
	v_mfma_f32_16x16x32_bf16 v[124:127], v[152:155], v[176:179], v[124:127]
	v_mfma_f32_16x16x32_bf16 v[120:123], v[168:171], v[176:179], v[120:123]
	v_mfma_f32_16x16x32_bf16 v[108:111], v[152:155], v[184:187], v[108:111]
	v_mfma_f32_16x16x32_bf16 v[104:107], v[168:171], v[184:187], v[104:107]
	v_mfma_f32_16x16x32_bf16 v[92:95], v[152:155], v[196:199], v[92:95]
	v_mfma_f32_16x16x32_bf16 v[88:91], v[168:171], v[196:199], v[88:91]
	v_mfma_f32_16x16x32_bf16 v[76:79], v[152:155], v[204:207], v[76:79]
	v_mfma_f32_16x16x32_bf16 v[72:75], v[168:171], v[204:207], v[72:75]
.Lz1_0_join:
	s_barrier
	s_add_i32 s93, s89, s57
	v_lshl_add_u64 v[156:157], s[52:53], 0, v[130:131]
	s_mov_b32 m0, s93
	ds_read_b128 v[208:211], v161
	ds_read_b128 v[212:215], v161 offset:1024
	ds_read_b128 v[216:219], v161 offset:2048
	ds_read_b128 v[220:223], v161 offset:3072
	global_load_lds_dwordx4 v[156:157], off
	v_lshl_add_u64 v[224:225], s[52:53], 0, v[134:135]
	s_add_i32 m0, s93, 0x2000
	s_nop 0
	global_load_lds_dwordx4 v[224:225], off
	s_barrier
	s_waitcnt lgkmcnt(0)
	s_waitcnt lgkmcnt(0)
	s_cmp_eq_u32 s92, -2
	s_cbranch_scc1 .Lz1_1_first
	v_mfma_f32_16x16x32_bf16 v[116:119], v[208:211], v[172:175], v[116:119]
	v_mfma_f32_16x16x32_bf16 v[112:115], v[216:219], v[172:175], v[112:115]
	v_mfma_f32_16x16x32_bf16 v[100:103], v[208:211], v[180:183], v[100:103]
	v_mfma_f32_16x16x32_bf16 v[96:99], v[216:219], v[180:183], v[96:99]
	v_mfma_f32_16x16x32_bf16 v[84:87], v[208:211], v[188:191], v[84:87]
	v_mfma_f32_16x16x32_bf16 v[80:83], v[216:219], v[188:191], v[80:83]
	v_mfma_f32_16x16x32_bf16 v[68:71], v[208:211], v[200:203], v[68:71]
	v_mfma_f32_16x16x32_bf16 v[64:67], v[216:219], v[200:203], v[64:67]
	v_mfma_f32_16x16x32_bf16 v[116:119], v[212:215], v[176:179], v[116:119]
	v_mfma_f32_16x16x32_bf16 v[112:115], v[220:223], v[176:179], v[112:115]
	v_mfma_f32_16x16x32_bf16 v[100:103], v[212:215], v[184:187], v[100:103]
	v_mfma_f32_16x16x32_bf16 v[96:99], v[220:223], v[184:187], v[96:99]
	v_mfma_f32_16x16x32_bf16 v[84:87], v[212:215], v[196:199], v[84:87]
	v_mfma_f32_16x16x32_bf16 v[80:83], v[220:223], v[196:199], v[80:83]
	v_mfma_f32_16x16x32_bf16 v[68:71], v[212:215], v[204:207], v[68:71]
	v_mfma_f32_16x16x32_bf16 v[64:67], v[220:223], v[204:207], v[64:67]
.Lz1_1_join:
	s_mov_b32 m0, s58
	v_lshl_add_u64 v[226:227], s[54:55], 0, v[128:129]
	s_barrier
	ds_read_b128 v[172:175], v160 offset:16384
	ds_read_b128 v[176:179], v160 offset:17408
	ds_read_b128 v[180:183], v160 offset:18432
	ds_read_b128 v[184:187], v160 offset:19456
	ds_read_b128 v[188:191], v160 offset:20480
	ds_read_b128 v[196:199], v160 offset:21504
	ds_read_b128 v[200:203], v160 offset:22528
	ds_read_b128 v[204:207], v160 offset:23552
	global_load_lds_dwordx4 v[226:227], off
	v_lshl_add_u64 v[228:229], s[54:55], 0, v[132:133]
	s_mov_b32 m0, s59
	s_nop 0
	global_load_lds_dwordx4 v[228:229], off
	s_barrier
	s_waitcnt lgkmcnt(0)
	s_waitcnt lgkmcnt(0)
	s_cmp_eq_u32 s92, -2
	s_cbranch_scc1 .Lz1_2_first
	v_mfma_f32_16x16x32_bf16 v[60:63], v[148:151], v[172:175], v[60:63]
	v_mfma_f32_16x16x32_bf16 v[56:59], v[164:167], v[172:175], v[56:59]
	v_mfma_f32_16x16x32_bf16 v[44:47], v[148:151], v[180:183], v[44:47]
	v_mfma_f32_16x16x32_bf16 v[40:43], v[164:167], v[180:183], v[40:43]
	v_mfma_f32_16x16x32_bf16 v[28:31], v[148:151], v[188:191], v[28:31]
	v_mfma_f32_16x16x32_bf16 v[24:27], v[164:167], v[188:191], v[24:27]
	v_mfma_f32_16x16x32_bf16 v[12:15], v[148:151], v[200:203], v[12:15]
	v_mfma_f32_16x16x32_bf16 v[8:11], v[164:167], v[200:203], v[8:11]
	v_mfma_f32_16x16x32_bf16 v[60:63], v[152:155], v[176:179], v[60:63]
	v_mfma_f32_16x16x32_bf16 v[56:59], v[168:171], v[176:179], v[56:59]
	v_mfma_f32_16x16x32_bf16 v[44:47], v[152:155], v[184:187], v[44:47]
	v_mfma_f32_16x16x32_bf16 v[40:43], v[168:171], v[184:187], v[40:43]
	v_mfma_f32_16x16x32_bf16 v[28:31], v[152:155], v[196:199], v[28:31]
	v_mfma_f32_16x16x32_bf16 v[24:27], v[168:171], v[196:199], v[24:27]
	v_mfma_f32_16x16x32_bf16 v[12:15], v[152:155], v[204:207], v[12:15]
	v_mfma_f32_16x16x32_bf16 v[8:11], v[168:171], v[204:207], v[8:11]
.Lz1_2_join:
	s_barrier
	s_add_u32 s94, s52, 0x10000
	s_addc_u32 s95, s53, 0
	s_add_i32 s93, s90, s57
	v_lshl_add_u64 v[148:149], s[94:95], 0, v[130:131]
	s_mov_b32 m0, s93
	s_nop 0
	global_load_lds_dwordx4 v[148:149], off
	v_lshl_add_u64 v[148:149], s[94:95], 0, v[134:135]
	s_add_i32 m0, s93, 0x2000
	s_nop 0
	global_load_lds_dwordx4 v[148:149], off
	s_cmp_eq_u32 s98, 0
	s_cbranch_scc1 .Lk1_w4n
	s_mov_b32 s98, 0
	s_waitcnt vmcnt(24)
	s_branch .Lk1_w4j

.Lk1_w4j:
	s_barrier
	s_cmp_eq_u32 s92, -2
	s_cbranch_scc1 .Lz1_3_first
	v_mfma_f32_16x16x32_bf16 v[52:55], v[208:211], v[172:175], v[52:55]
	v_mfma_f32_16x16x32_bf16 v[48:51], v[216:219], v[172:175], v[48:51]
	v_mfma_f32_16x16x32_bf16 v[36:39], v[208:211], v[180:183], v[36:39]
	v_mfma_f32_16x16x32_bf16 v[32:35], v[216:219], v[180:183], v[32:35]
	v_mfma_f32_16x16x32_bf16 v[20:23], v[208:211], v[188:191], v[20:23]
	v_mfma_f32_16x16x32_bf16 v[16:19], v[216:219], v[188:191], v[16:19]
	v_mfma_f32_16x16x32_bf16 v[4:7], v[208:211], v[200:203], v[4:7]
	v_mfma_f32_16x16x32_bf16 v[0:3], v[216:219], v[200:203], v[0:3]
	v_mfma_f32_16x16x32_bf16 v[52:55], v[212:215], v[176:179], v[52:55]
	v_mfma_f32_16x16x32_bf16 v[48:51], v[220:223], v[176:179], v[48:51]
	v_mfma_f32_16x16x32_bf16 v[36:39], v[212:215], v[184:187], v[36:39]
	v_mfma_f32_16x16x32_bf16 v[32:35], v[220:223], v[184:187], v[32:35]
	v_mfma_f32_16x16x32_bf16 v[20:23], v[212:215], v[196:199], v[20:23]
	v_mfma_f32_16x16x32_bf16 v[16:19], v[220:223], v[196:199], v[16:19]
	v_mfma_f32_16x16x32_bf16 v[4:7], v[212:215], v[204:207], v[4:7]
	v_mfma_f32_16x16x32_bf16 v[0:3], v[220:223], v[204:207], v[0:3]
.Lz1_3_join:
	s_add_i32 s93, 0, 0x18000
	v_add_u32_e32 v136, s93, v158
	s_barrier
	ds_read_b128 v[148:151], v136
	ds_read_b128 v[152:155], v136 offset:1024
	ds_read_b128 v[164:167], v136 offset:2048
	ds_read_b128 v[168:171], v136 offset:3072
	s_add_u32 s54, s54, 0x40000
	s_addc_u32 s55, s55, 0
	s_mov_b32 m0, s60
	v_lshl_add_u64 v[208:209], s[54:55], 0, v[128:129]
	ds_read_b128 v[172:175], v160 offset:32768
	ds_read_b128 v[176:179], v160 offset:33792
	ds_read_b128 v[180:183], v160 offset:34816
	ds_read_b128 v[184:187], v160 offset:35840
	ds_read_b128 v[188:191], v160 offset:36864
	ds_read_b128 v[196:199], v160 offset:37888
	ds_read_b128 v[200:203], v160 offset:38912
	ds_read_b128 v[204:207], v160 offset:39936
	global_load_lds_dwordx4 v[208:209], off
	v_lshl_add_u64 v[208:209], s[54:55], 0, v[132:133]
	s_mov_b32 m0, s61
	s_nop 0
	global_load_lds_dwordx4 v[208:209], off
	s_waitcnt lgkmcnt(8)
	s_barrier
	s_waitcnt lgkmcnt(0)
	s_waitcnt lgkmcnt(0)
	v_mfma_f32_16x16x32_bf16 v[124:127], v[148:151], v[172:175], v[124:127]
	v_mfma_f32_16x16x32_bf16 v[120:123], v[164:167], v[172:175], v[120:123]
	v_mfma_f32_16x16x32_bf16 v[108:111], v[148:151], v[180:183], v[108:111]
	v_mfma_f32_16x16x32_bf16 v[104:107], v[164:167], v[180:183], v[104:107]
	v_mfma_f32_16x16x32_bf16 v[92:95], v[148:151], v[188:191], v[92:95]
	v_mfma_f32_16x16x32_bf16 v[88:91], v[164:167], v[188:191], v[88:91]
	v_mfma_f32_16x16x32_bf16 v[76:79], v[148:151], v[200:203], v[76:79]
	v_mfma_f32_16x16x32_bf16 v[72:75], v[164:167], v[200:203], v[72:75]
	v_mfma_f32_16x16x32_bf16 v[124:127], v[152:155], v[176:179], v[124:127]
	v_mfma_f32_16x16x32_bf16 v[120:123], v[168:171], v[176:179], v[120:123]
	v_mfma_f32_16x16x32_bf16 v[108:111], v[152:155], v[184:187], v[108:111]
	v_mfma_f32_16x16x32_bf16 v[104:107], v[168:171], v[184:187], v[104:107]
	v_mfma_f32_16x16x32_bf16 v[92:95], v[152:155], v[196:199], v[92:95]
	v_mfma_f32_16x16x32_bf16 v[88:91], v[168:171], v[196:199], v[88:91]
	v_mfma_f32_16x16x32_bf16 v[76:79], v[152:155], v[204:207], v[76:79]
	v_mfma_f32_16x16x32_bf16 v[72:75], v[168:171], v[204:207], v[72:75]
	s_barrier
	s_add_i32 s54, 0, 0x1c000
	s_add_i32 s55, s93, s57
	v_add_u32_e32 v136, s54, v158
	v_lshl_add_u64 v[156:157], v[156:157], 0, s[0:1]
	s_mov_b32 m0, s55
	ds_read_b128 v[208:211], v136
	ds_read_b128 v[212:215], v136 offset:1024
	ds_read_b128 v[216:219], v136 offset:2048
	ds_read_b128 v[220:223], v136 offset:3072
	global_load_lds_dwordx4 v[156:157], off
	v_lshl_add_u64 v[156:157], v[224:225], 0, s[0:1]
	s_add_i32 m0, s55, 0x2000
	s_nop 0
	global_load_lds_dwordx4 v[156:157], off
	s_barrier
	s_waitcnt lgkmcnt(0)
	s_waitcnt lgkmcnt(0)
	v_mfma_f32_16x16x32_bf16 v[116:119], v[208:211], v[172:175], v[116:119]
	v_mfma_f32_16x16x32_bf16 v[112:115], v[216:219], v[172:175], v[112:115]
	v_mfma_f32_16x16x32_bf16 v[100:103], v[208:211], v[180:183], v[100:103]
	v_mfma_f32_16x16x32_bf16 v[96:99], v[216:219], v[180:183], v[96:99]
	v_mfma_f32_16x16x32_bf16 v[84:87], v[208:211], v[188:191], v[84:87]
	v_mfma_f32_16x16x32_bf16 v[80:83], v[216:219], v[188:191], v[80:83]
	v_mfma_f32_16x16x32_bf16 v[68:71], v[208:211], v[200:203], v[68:71]
	v_mfma_f32_16x16x32_bf16 v[64:67], v[216:219], v[200:203], v[64:67]
	v_mfma_f32_16x16x32_bf16 v[116:119], v[212:215], v[176:179], v[116:119]
	v_mfma_f32_16x16x32_bf16 v[112:115], v[220:223], v[176:179], v[112:115]
	v_mfma_f32_16x16x32_bf16 v[100:103], v[212:215], v[184:187], v[100:103]
	v_mfma_f32_16x16x32_bf16 v[96:99], v[220:223], v[184:187], v[96:99]
	v_mfma_f32_16x16x32_bf16 v[84:87], v[212:215], v[196:199], v[84:87]
	v_mfma_f32_16x16x32_bf16 v[80:83], v[220:223], v[196:199], v[80:83]
	v_mfma_f32_16x16x32_bf16 v[68:71], v[212:215], v[204:207], v[68:71]
	v_mfma_f32_16x16x32_bf16 v[64:67], v[220:223], v[204:207], v[64:67]
	s_mov_b32 m0, s65
	v_lshl_add_u64 v[156:157], v[226:227], 0, s[0:1]
	s_waitcnt vmcnt(10)
	s_barrier
	ds_read_b128 v[172:175], v160 offset:49152
	ds_read_b128 v[176:179], v160 offset:50176
	ds_read_b128 v[180:183], v160 offset:51200
	ds_read_b128 v[184:187], v160 offset:52224
	ds_read_b128 v[188:191], v160 offset:53248
	ds_read_b128 v[196:199], v160 offset:54272
	ds_read_b128 v[200:203], v160 offset:55296
	ds_read_b128 v[204:207], v160 offset:56320
	global_load_lds_dwordx4 v[156:157], off
	v_lshl_add_u64 v[156:157], v[228:229], 0, s[0:1]
	s_mov_b32 m0, s66
	s_nop 0
	global_load_lds_dwordx4 v[156:157], off
	s_barrier
	s_waitcnt lgkmcnt(0)
	s_waitcnt lgkmcnt(0)
	v_mfma_f32_16x16x32_bf16 v[60:63], v[148:151], v[172:175], v[60:63]
	v_mfma_f32_16x16x32_bf16 v[56:59], v[164:167], v[172:175], v[56:59]
	v_mfma_f32_16x16x32_bf16 v[44:47], v[148:151], v[180:183], v[44:47]
	v_mfma_f32_16x16x32_bf16 v[40:43], v[164:167], v[180:183], v[40:43]
	v_mfma_f32_16x16x32_bf16 v[28:31], v[148:151], v[188:191], v[28:31]
	v_mfma_f32_16x16x32_bf16 v[24:27], v[164:167], v[188:191], v[24:27]
	v_mfma_f32_16x16x32_bf16 v[12:15], v[148:151], v[200:203], v[12:15]
	v_mfma_f32_16x16x32_bf16 v[8:11], v[164:167], v[200:203], v[8:11]
	v_mfma_f32_16x16x32_bf16 v[60:63], v[152:155], v[176:179], v[60:63]
	v_mfma_f32_16x16x32_bf16 v[56:59], v[168:171], v[176:179], v[56:59]
	v_mfma_f32_16x16x32_bf16 v[44:47], v[152:155], v[184:187], v[44:47]
	v_mfma_f32_16x16x32_bf16 v[40:43], v[168:171], v[184:187], v[40:43]
	v_mfma_f32_16x16x32_bf16 v[28:31], v[152:155], v[196:199], v[28:31]
	v_mfma_f32_16x16x32_bf16 v[24:27], v[168:171], v[196:199], v[24:27]
	v_mfma_f32_16x16x32_bf16 v[12:15], v[152:155], v[204:207], v[12:15]
	v_mfma_f32_16x16x32_bf16 v[8:11], v[168:171], v[204:207], v[8:11]
	s_barrier
	s_add_u32 s52, s52, 0x10080
	s_addc_u32 s53, s53, 0
	s_add_i32 s54, s54, s57
	v_lshl_add_u64 v[148:149], s[52:53], 0, v[130:131]
	s_mov_b32 m0, s54
	s_nop 0
	global_load_lds_dwordx4 v[148:149], off
	v_lshl_add_u64 v[148:149], s[52:53], 0, v[134:135]
	s_add_i32 m0, s54, 0x2000
	s_nop 0
	global_load_lds_dwordx4 v[148:149], off
	s_waitcnt vmcnt(6)
	s_barrier
	v_mfma_f32_16x16x32_bf16 v[52:55], v[208:211], v[172:175], v[52:55]
	v_mfma_f32_16x16x32_bf16 v[48:51], v[216:219], v[172:175], v[48:51]
	v_mfma_f32_16x16x32_bf16 v[36:39], v[208:211], v[180:183], v[36:39]
	v_mfma_f32_16x16x32_bf16 v[32:35], v[216:219], v[180:183], v[32:35]
	v_mfma_f32_16x16x32_bf16 v[20:23], v[208:211], v[188:191], v[20:23]
	v_mfma_f32_16x16x32_bf16 v[16:19], v[216:219], v[188:191], v[16:19]
	v_mfma_f32_16x16x32_bf16 v[4:7], v[208:211], v[200:203], v[4:7]
	v_mfma_f32_16x16x32_bf16 v[0:3], v[216:219], v[200:203], v[0:3]
	v_mfma_f32_16x16x32_bf16 v[52:55], v[212:215], v[176:179], v[52:55]
	v_mfma_f32_16x16x32_bf16 v[48:51], v[220:223], v[176:179], v[48:51]
	v_mfma_f32_16x16x32_bf16 v[36:39], v[212:215], v[184:187], v[36:39]
	v_mfma_f32_16x16x32_bf16 v[32:35], v[220:223], v[184:187], v[32:35]
	v_mfma_f32_16x16x32_bf16 v[20:23], v[212:215], v[196:199], v[20:23]
	v_mfma_f32_16x16x32_bf16 v[16:19], v[220:223], v[196:199], v[16:19]
	v_mfma_f32_16x16x32_bf16 v[4:7], v[212:215], v[204:207], v[4:7]
	v_mfma_f32_16x16x32_bf16 v[0:3], v[220:223], v[204:207], v[0:3]
	s_add_i32 s92, s92, 2
	s_add_u32 s50, s50, 0x100
	s_addc_u32 s51, s51, 0
	s_add_u32 s45, s45, 0x100
	s_addc_u32 s91, s91, 0
	s_cmp_gt_u32 s92, 13
	s_barrier
	s_cbranch_scc0 .LBB0_178
	s_branch .Lz1_skip

.LBB0_275:
	s_setprio 0
	s_waitcnt vmcnt(0)
	s_cmpk_gt_u32 s56, 0xff
	s_cbranch_scc1 .LBB0_277
	s_barrier

.LBB0_1089:
	s_lshl_b32 s5, s6, 5
	s_mov_b64 s[6:7], 0x80
	s_and_b32 s10, s5, 0x60
	s_add_i32 m0, s47, 0x18000
	v_lshl_add_u64 v[6:7], v[6:7], 0, s[6:7]
	s_ashr_i32 s52, s90, 31
	s_lshl_b32 s8, s3, 13
	s_lshl_b32 s28, s10, 7
	s_waitcnt vmcnt(4)
	s_barrier
	global_load_lds_dwordx4 v[6:7], off
	v_lshl_add_u64 v[4:5], v[4:5], 0, s[6:7]
	s_add_i32 m0, s47, 0x1a000
	s_add_i32 s53, s47, 0x8000
	s_add_i32 s54, s47, 0xa000
	global_load_lds_dwordx4 v[4:5], off
	v_lshl_add_u64 v[2:3], v[2:3], 0, s[6:7]
	s_mov_b32 m0, s53
	s_add_u32 s12, s42, 0x40080
	global_load_lds_dwordx4 v[2:3], off
	v_lshl_add_u64 v[0:1], v[0:1], 0, s[6:7]
	s_mov_b32 m0, s54
	s_addc_u32 s13, s43, 0
	global_load_lds_dwordx4 v[0:1], off
	s_add_i32 m0, s47, 0x1c000
	v_lshl_add_u64 v[0:1], s[12:13], 0, v[132:133]
	global_load_lds_dwordx4 v[0:1], off
	v_lshl_add_u64 v[0:1], s[12:13], 0, v[128:129]
	s_add_i32 m0, s47, 0x1e000
	v_bfe_u32 v2, v9, 4, 2
	global_load_lds_dwordx4 v[0:1], off
	v_and_b32_e32 v1, 15, v9
	v_lshlrev_b32_e32 v0, 4, v2
	v_lshlrev_b32_e32 v3, 2, v9
	v_lshl_or_b32 v155, s3, 6, v1
	v_lshl_or_b32 v1, v1, 6, v0
	v_and_b32_e32 v3, 32, v3
	v_bitop3_b32 v4, v1, s8, v3 bitop3:0xde
	v_bitop3_b32 v159, v1, s28, v3 bitop3:0xde
	v_mov_b32_e32 v1, v133
	v_lshl_add_u64 v[136:137], s[0:1], 0, v[0:1]
	v_lshlrev_b32_e32 v0, 14, v13
	v_and_b32_e32 v0, 0xffff8000, v0
	v_lshl_add_u32 v0, v12, 11, v0
	v_and_b32_e32 v1, 1, v13
	v_lshl_or_b32 v0, v1, 6, v0
	v_lshl_add_u32 v138, v14, 1, v0
	v_lshlrev_b32_e32 v0, 14, v8
	v_and_b32_e32 v0, 0xffff8000, v0
	v_lshl_add_u32 v0, v10, 11, v0
	v_and_b32_e32 v1, 1, v8
	s_waitcnt vmcnt(6)
	v_lshl_or_b32 v0, v1, 6, v0
	v_lshl_add_u32 v140, v11, 1, v0
	s_add_i32 s56, 0, 0x10000
	s_add_i32 s57, 0, 0x14000
	v_mbcnt_lo_u32_b32 v0, -1, 0
	s_sext_i32_i8 s5, s2
	s_mov_b32 s55, s90
	v_lshl_or_b32 v163, v2, 3, s10
	v_mov_b32_e32 v139, v133
	v_mov_b32_e32 v141, v133
	v_mov_b64_e32 v[142:143], 0xb00
	v_mov_b64_e32 v[144:145], 0xaff
	v_add_u32_e32 v167, s56, v159
	v_add_u32_e32 v171, 0, v4
	v_add_u32_e32 v175, s57, v159
	v_mbcnt_hi_u32_b32 v177, -1, v0
	s_mov_b32 s8, 0x3a800000
	s_mov_b32 s10, 0x358637bd
	s_mov_b32 s58, 0x800000
	s_movk_i32 s59, 0x1600
	s_mov_b32 s96, s4
	s_mov_b32 s97, s5
	v_lshl_add_u32 v168, s4, 8, v155
	v_ashrrev_i32_e32 v169, 31, v168
	v_or_b32_e32 v164, 16, v168
	v_lshlrev_b64 v[146:147], 6, v[168:169]
	v_ashrrev_i32_e32 v165, 31, v164
	v_or_b32_e32 v160, 32, v168
	v_lshl_add_u64 v[146:147], v[136:137], 0, v[146:147]
	v_lshlrev_b64 v[148:149], 6, v[164:165]
	v_ashrrev_i32_e32 v161, 31, v160
	v_lshl_add_u64 v[148:149], v[136:137], 0, v[148:149]
	global_load_dwordx4 v[178:181], v[146:147], off
	global_load_dwordx4 v[182:185], v[148:149], off
	v_lshlrev_b64 v[146:147], 6, v[160:161]
	v_or_b32_e32 v156, 48, v168
	v_lshl_add_u64 v[146:147], v[136:137], 0, v[146:147]
	v_ashrrev_i32_e32 v157, 31, v156
	global_load_dwordx4 v[186:189], v[146:147], off
	v_lshlrev_b64 v[146:147], 6, v[156:157]
	v_lshl_add_u64 v[146:147], v[136:137], 0, v[146:147]
	global_load_dwordx4 v[196:199], v[146:147], off
	v_add_u32_e32 v152, 0x80, v168
	v_ashrrev_i32_e32 v153, 31, v152
	v_lshlrev_b64 v[146:147], 6, v[152:153]
	v_add_u32_e32 v150, 0x90, v168
	v_lshl_add_u64 v[146:147], v[136:137], 0, v[146:147]
	v_ashrrev_i32_e32 v151, 31, v150
	global_load_dwordx4 v[200:203], v[146:147], off
	v_lshlrev_b64 v[146:147], 6, v[150:151]
	v_lshl_add_u64 v[146:147], v[136:137], 0, v[146:147]
	global_load_dwordx4 v[204:207], v[146:147], off
	v_and_b32_e32 v147, 64, v177
	v_add_u32_e32 v148, 0xa0, v168
	v_add_u32_e32 v146, 0xb0, v168
	v_add_u32_e32 v154, 64, v147
	v_ashrrev_i32_e32 v149, 31, v148
	v_ashrrev_i32_e32 v147, 31, v146
	v_lshlrev_b64 v[208:209], 6, v[148:149]
	v_lshlrev_b64 v[210:211], 6, v[146:147]
	v_lshl_add_u64 v[208:209], v[136:137], 0, v[208:209]
	v_lshl_add_u64 v[212:213], v[136:137], 0, v[210:211]
	global_load_dwordx4 v[208:211], v[208:209], off
	s_nop 0
	global_load_dwordx4 v[212:215], v[212:213], off
	v_xor_b32_e32 v151, 16, v177
	v_cmp_lt_i32_e32 vcc, v151, v154
	v_xor_b32_e32 v153, 32, v177
	v_mov_b64_e32 v[190:191], s[10:11]
	v_cndmask_b32_e32 v151, v177, v151, vcc
	v_lshlrev_b32_e32 v147, 2, v151
	v_cmp_lt_i32_e32 vcc, v153, v154
	v_lshl_or_b32 v172, s5, 7, v163
	s_waitcnt vmcnt(0)
	v_mov_b32_e32 v216, v179
	v_mov_b32_e32 v217, v180
	v_mov_b32_e32 v179, v181
	v_mov_b32_e32 v180, v183
	v_mov_b32_e32 v181, v184
	v_mov_b32_e32 v183, v185
	v_pk_add_f32 v[178:179], v[216:217], v[178:179]
	v_pk_add_f32 v[180:181], v[180:181], v[182:183]
	v_mov_b32_e32 v183, v178
	v_mov_b32_e32 v182, v180
	v_mov_b32_e32 v178, v181
	v_mov_b32_e32 v184, v187
	v_mov_b32_e32 v185, v188
	v_mov_b32_e32 v187, v189
	v_mov_b32_e32 v188, v197
	v_mov_b32_e32 v189, v198
	v_mov_b32_e32 v197, v199
	v_pk_add_f32 v[178:179], v[182:183], v[178:179]
	v_pk_add_f32 v[184:185], v[184:185], v[186:187]
	v_pk_add_f32 v[186:187], v[188:189], v[196:197]
	ds_bpermute_b32 v183, v147, v179
	ds_bpermute_b32 v182, v147, v178
	v_mov_b32_e32 v180, v186
	v_mov_b32_e32 v181, v184
	v_mov_b32_e32 v184, v187
	v_pk_add_f32 v[180:181], v[180:181], v[184:185]
	ds_bpermute_b32 v185, v147, v181
	ds_bpermute_b32 v184, v147, v180
	v_cndmask_b32_e32 v153, v177, v153, vcc
	v_lshlrev_b32_e32 v149, 2, v153
	s_waitcnt lgkmcnt(0)
	v_pk_add_f32 v[178:179], v[178:179], v[182:183]
	ds_bpermute_b32 v183, v149, v179
	ds_bpermute_b32 v182, v149, v178
	v_pk_add_f32 v[180:181], v[180:181], v[184:185]
	ds_bpermute_b32 v185, v149, v181
	ds_bpermute_b32 v184, v149, v180
	v_mov_b32_e32 v186, v201
	s_waitcnt lgkmcnt(2)
	v_pk_add_f32 v[178:179], v[178:179], v[182:183]
	v_mov_b32_e32 v187, v202
	v_mov_b32_e32 v201, v203
	v_mov_b32_e32 v188, v205
	v_pk_fma_f32 v[178:179], v[178:179], s[8:9], v[190:191] op_sel_hi:[1,0,0]
	v_mov_b32_e32 v189, v206
	v_mov_b32_e32 v205, v207
	v_pk_add_f32 v[186:187], v[186:187], v[200:201]
	v_mul_f32_e32 v151, 0x4b800000, v179
	v_cmp_gt_f32_e32 vcc, s58, v179
	v_pk_add_f32 v[182:183], v[188:189], v[204:205]
	s_waitcnt lgkmcnt(0)
	v_pk_add_f32 v[180:181], v[180:181], v[184:185]
	v_cndmask_b32_e32 v151, v179, v151, vcc
	v_mov_b32_e32 v184, v182
	v_mov_b32_e32 v185, v186
	v_mov_b32_e32 v186, v183
	v_rsq_f32_e32 v151, v151
	v_pk_add_f32 v[182:183], v[184:185], v[186:187]
	ds_bpermute_b32 v185, v147, v183
	ds_bpermute_b32 v184, v147, v182
	v_pk_fma_f32 v[180:181], v[180:181], s[8:9], v[190:191] op_sel_hi:[1,0,0]
	v_mul_f32_e32 v153, 0x4b800000, v178
	v_cmp_gt_f32_e64 s[0:1], s58, v178
	v_mul_f32_e32 v157, 0x45800000, v151
	v_mul_f32_e32 v154, 0x4b800000, v181
	v_cndmask_b32_e64 v153, v178, v153, s[0:1]
	v_cmp_gt_f32_e64 s[4:5], s58, v181
	v_cndmask_b32_e32 v178, v151, v157, vcc
	v_mul_f32_e32 v151, 0x4b800000, v180
	v_cmp_gt_f32_e32 vcc, s58, v180
	v_cndmask_b32_e64 v154, v181, v154, s[4:5]
	v_rsq_f32_e32 v153, v153
	v_cndmask_b32_e32 v151, v180, v151, vcc
	s_waitcnt lgkmcnt(0)
	v_pk_add_f32 v[180:181], v[182:183], v[184:185]
	ds_bpermute_b32 v183, v149, v181
	ds_bpermute_b32 v182, v149, v180
	v_mov_b32_e32 v184, v213
	v_mov_b32_e32 v185, v214
	v_mov_b32_e32 v213, v215
	v_pk_add_f32 v[184:185], v[184:185], v[212:213]
	s_waitcnt lgkmcnt(0)
	v_pk_add_f32 v[180:181], v[180:181], v[182:183]
	v_mov_b32_e32 v182, v209
	v_mov_b32_e32 v183, v210
	v_mov_b32_e32 v209, v211
	v_pk_add_f32 v[182:183], v[182:183], v[208:209]
	v_mov_b32_e32 v186, v184
	v_mov_b32_e32 v187, v182
	v_mov_b32_e32 v182, v185
	v_rsq_f32_e32 v154, v154
	v_pk_add_f32 v[182:183], v[186:187], v[182:183]
	ds_bpermute_b32 v185, v147, v183
	ds_bpermute_b32 v184, v147, v182
	v_mul_f32_e32 v158, 0x45800000, v153
	v_cndmask_b32_e64 v176, v153, v158, s[0:1]
	v_mul_f32_e32 v153, 0x45800000, v154
	v_pk_fma_f32 v[180:181], v[180:181], s[8:9], v[190:191] op_sel_hi:[1,0,0]
	v_cndmask_b32_e64 v174, v154, v153, s[4:5]
	v_mul_f32_e32 v154, 0x4b800000, v181
	v_cmp_gt_f32_e64 s[0:1], s58, v181
	v_mul_f32_e32 v147, 0x4b800000, v180
	v_cmp_gt_f32_e64 s[4:5], s58, v180
	v_cndmask_b32_e64 v154, v181, v154, s[0:1]
	v_rsq_f32_e32 v151, v151
	v_cndmask_b32_e64 v147, v180, v147, s[4:5]
	s_waitcnt lgkmcnt(0)
	v_pk_add_f32 v[180:181], v[182:183], v[184:185]
	ds_bpermute_b32 v183, v149, v181
	ds_bpermute_b32 v182, v149, v180
	v_rsq_f32_e32 v154, v154
	v_mul_f32_e32 v153, 0x45800000, v151
	v_cndmask_b32_e32 v170, v151, v153, vcc
	v_rsq_f32_e32 v147, v147
	s_waitcnt lgkmcnt(0)
	v_pk_add_f32 v[180:181], v[180:181], v[182:183]
	v_mul_f32_e32 v149, 0x45800000, v154
	v_pk_fma_f32 v[180:181], v[180:181], s[8:9], v[190:191] op_sel_hi:[1,0,0]
	v_cndmask_b32_e64 v166, v154, v149, s[0:1]
	v_mul_f32_e32 v151, 0x4b800000, v181
	v_cmp_gt_f32_e32 vcc, s58, v181
	v_mul_f32_e32 v153, 0x4b800000, v180
	v_cmp_gt_f32_e64 s[0:1], s58, v180
	v_cndmask_b32_e32 v151, v181, v151, vcc
	v_rsq_f32_e32 v151, v151
	v_cndmask_b32_e64 v153, v180, v153, s[0:1]
	v_rsq_f32_e32 v153, v153
	v_mul_f32_e32 v149, 0x45800000, v147
	v_cndmask_b32_e64 v162, v147, v149, s[4:5]
	v_mul_f32_e32 v147, 0x45800000, v151
	v_cndmask_b32_e32 v158, v151, v147, vcc
	v_mul_f32_e32 v147, 0x45800000, v153
	v_cndmask_b32_e64 v154, v153, v147, s[0:1]
	v_mov_b32_e32 v240, v178
	v_mov_b32_e32 v241, v154
	s_mov_b32 s4, s96
	s_mov_b32 s5, s97
	s_barrier
	s_cmpk_gt_u32 s9, 0xff
	s_cbranch_scc0 .Lpr_lbb0_1093
	s_setprio 1
.Lpr_lbb0_1093:
.LBB0_1090:
	s_add_i32 s51, s51, 1
	s_mul_i32 s0, s51, s52
	s_mul_hi_u32 s1, s51, s55
	s_add_i32 s1, s1, s0
	s_mul_i32 s0, s51, s55
	s_add_u32 s0, s0, s16
	s_addc_u32 s1, s1, s17
	v_cmp_gt_i64_e64 s[2:3], s[0:1], v[144:145]
	s_and_b64 vcc, exec, s[2:3]
	s_cbranch_vccnz .LBB0_1092
	s_ashr_i32 s12, s0, 31
	s_lshr_b32 s12, s12, 29
	s_add_i32 s12, s0, s12
	s_ashr_i32 s13, s12, 3
	s_and_b32 s12, s12, -8
	s_sub_i32 s12, s0, s12
	s_cmp_lt_i32 s12, 0
	s_cselect_b32 s28, s46, 0x160
	s_mul_i32 s12, s12, s28
	s_add_i32 s12, s12, s13
	s_mul_hi_i32 s13, s12, 0x2e8ba2e9
	s_lshr_b32 s28, s13, 31
	s_ashr_i32 s13, s13, 4
	s_add_i32 s13, s13, s28
	s_lshl_b32 s28, s13, 2
	s_sub_i32 s29, 0x80, s28
	s_min_i32 s29, s29, 4
	s_abs_i32 s36, s29
	v_cvt_f32_u32_e32 v0, s36
	s_sub_i32 s38, 0, s36
	s_mulk_i32 s13, 0x58
	s_sub_i32 s13, s12, s13
	v_rcp_iflag_f32_e32 v0, v0
	s_abs_i32 s12, s13
	s_xor_b32 s37, s13, s29
	s_ashr_i32 s37, s37, 31
	v_mul_f32_e32 v0, 0x4f7ffffe, v0
	v_cvt_u32_f32_e32 v0, v0
	s_nop 0
	v_readfirstlane_b32 s39, v0
	s_mul_i32 s38, s38, s39
	s_mul_hi_u32 s38, s39, s38
	s_add_i32 s39, s39, s38
	s_mul_hi_u32 s38, s12, s39
	s_mul_i32 s39, s38, s36
	s_sub_i32 s12, s12, s39
	s_add_i32 s40, s38, 1
	s_sub_i32 s39, s12, s36
	s_cmp_ge_u32 s12, s36
	s_cselect_b32 s38, s40, s38
	s_cselect_b32 s12, s39, s12
	s_add_i32 s39, s38, 1
	s_cmp_ge_u32 s12, s36
	s_cselect_b32 s12, s39, s38
	s_xor_b32 s12, s12, s37
	s_sub_i32 s12, s12, s37
	s_mul_i32 s29, s12, s29
	s_sub_i32 s13, s13, s29
	s_add_i32 s36, s28, s13

.LBB0_1093:
	ds_read_b128 v[146:149], v167
	ds_read_b128 v[150:153], v167 offset:1024
	ds_read_b128 v[178:181], v167 offset:2048
	ds_read_b128 v[182:185], v167 offset:3072
	s_add_u32 s28, s0, 0xfffc0080
	s_addc_u32 s29, s1, -1
	s_cmp_eq_u32 s64, 12
	s_cselect_b32 s45, s37, s29
	s_cselect_b32 s44, s60, s28
	s_cselect_b32 s43, s13, s63
	s_cselect_b32 s42, s61, s62
	v_lshl_add_u64 v[156:157], s[0:1], 0, v[138:139]
	s_add_i32 m0, s47, 0xc000
	ds_read_b128 v[186:189], v171
	ds_read_b128 v[196:199], v171 offset:1024
	ds_read_b128 v[200:203], v171 offset:2048
	ds_read_b128 v[204:207], v171 offset:3072
	ds_read_b128 v[208:211], v171 offset:4096
	ds_read_b128 v[212:215], v171 offset:5120
	ds_read_b128 v[216:219], v171 offset:6144
	ds_read_b128 v[220:223], v171 offset:7168
	global_load_lds_dwordx4 v[156:157], off
	v_lshl_add_u64 v[156:157], s[0:1], 0, v[140:141]
	s_add_i32 m0, s47, 0xe000
	s_nop 0
	global_load_lds_dwordx4 v[156:157], off
	s_waitcnt lgkmcnt(8)
	s_barrier
	s_waitcnt lgkmcnt(0)
	s_waitcnt lgkmcnt(0)
	s_cmp_eq_u32 s64, -2
	s_cbranch_scc1 .Lz10_0_first
	v_mfma_f32_16x16x32_bf16 v[124:127], v[146:149], v[186:189], v[124:127]
	v_mfma_f32_16x16x32_bf16 v[120:123], v[178:181], v[186:189], v[120:123]
	v_mfma_f32_16x16x32_bf16 v[108:111], v[146:149], v[200:203], v[108:111]
	v_mfma_f32_16x16x32_bf16 v[104:107], v[178:181], v[200:203], v[104:107]
	v_mfma_f32_16x16x32_bf16 v[92:95], v[146:149], v[208:211], v[92:95]
	v_mfma_f32_16x16x32_bf16 v[88:91], v[178:181], v[208:211], v[88:91]
	v_mfma_f32_16x16x32_bf16 v[76:79], v[146:149], v[216:219], v[76:79]
	v_mfma_f32_16x16x32_bf16 v[72:75], v[178:181], v[216:219], v[72:75]
	v_mfma_f32_16x16x32_bf16 v[124:127], v[150:153], v[196:199], v[124:127]
	v_mfma_f32_16x16x32_bf16 v[120:123], v[182:185], v[196:199], v[120:123]
	v_mfma_f32_16x16x32_bf16 v[108:111], v[150:153], v[204:207], v[108:111]
	v_mfma_f32_16x16x32_bf16 v[104:107], v[182:185], v[204:207], v[104:107]
	v_mfma_f32_16x16x32_bf16 v[92:95], v[150:153], v[212:215], v[92:95]
	v_mfma_f32_16x16x32_bf16 v[88:91], v[182:185], v[212:215], v[88:91]
	v_mfma_f32_16x16x32_bf16 v[76:79], v[150:153], v[220:223], v[76:79]
	v_mfma_f32_16x16x32_bf16 v[72:75], v[182:185], v[220:223], v[72:75]
.Lz10_0_join:
	s_barrier
	s_add_i32 s28, s56, s11
	v_lshl_add_u64 v[156:157], s[42:43], 0, v[132:133]
	s_mov_b32 m0, s28
	ds_read_b128 v[224:227], v175
	ds_read_b128 v[228:231], v175 offset:1024
	ds_read_b128 v[232:235], v175 offset:2048
	ds_read_b128 v[236:239], v175 offset:3072
	global_load_lds_dwordx4 v[156:157], off
	v_lshl_add_u64 v[160:161], s[42:43], 0, v[128:129]
	s_add_i32 m0, s28, 0x2000
	s_nop 0
	global_load_lds_dwordx4 v[160:161], off
	s_barrier
	s_waitcnt lgkmcnt(0)
	s_waitcnt lgkmcnt(0)
	s_cmp_eq_u32 s64, -2
	s_cbranch_scc1 .Lz10_1_first
	v_mfma_f32_16x16x32_bf16 v[116:119], v[224:227], v[186:189], v[116:119]
	v_mfma_f32_16x16x32_bf16 v[112:115], v[232:235], v[186:189], v[112:115]
	v_mfma_f32_16x16x32_bf16 v[100:103], v[224:227], v[200:203], v[100:103]
	v_mfma_f32_16x16x32_bf16 v[96:99], v[232:235], v[200:203], v[96:99]
	v_mfma_f32_16x16x32_bf16 v[84:87], v[224:227], v[208:211], v[84:87]
	v_mfma_f32_16x16x32_bf16 v[80:83], v[232:235], v[208:211], v[80:83]
	v_mfma_f32_16x16x32_bf16 v[68:71], v[224:227], v[216:219], v[68:71]
	v_mfma_f32_16x16x32_bf16 v[64:67], v[232:235], v[216:219], v[64:67]
	v_mfma_f32_16x16x32_bf16 v[116:119], v[228:231], v[196:199], v[116:119]
	v_mfma_f32_16x16x32_bf16 v[112:115], v[236:239], v[196:199], v[112:115]
	v_mfma_f32_16x16x32_bf16 v[100:103], v[228:231], v[204:207], v[100:103]
	v_mfma_f32_16x16x32_bf16 v[96:99], v[236:239], v[204:207], v[96:99]
	v_mfma_f32_16x16x32_bf16 v[84:87], v[228:231], v[212:215], v[84:87]
	v_mfma_f32_16x16x32_bf16 v[80:83], v[236:239], v[212:215], v[80:83]
	v_mfma_f32_16x16x32_bf16 v[68:71], v[228:231], v[220:223], v[68:71]
	v_mfma_f32_16x16x32_bf16 v[64:67], v[236:239], v[220:223], v[64:67]
.Lz10_1_join:
	s_mov_b32 m0, s47
	v_lshl_add_u64 v[164:165], s[44:45], 0, v[134:135]
	s_barrier
	ds_read_b128 v[186:189], v171 offset:16384
	ds_read_b128 v[196:199], v171 offset:17408
	ds_read_b128 v[200:203], v171 offset:18432
	ds_read_b128 v[204:207], v171 offset:19456
	ds_read_b128 v[208:211], v171 offset:20480
	ds_read_b128 v[212:215], v171 offset:21504
	ds_read_b128 v[216:219], v171 offset:22528
	ds_read_b128 v[220:223], v171 offset:23552
	global_load_lds_dwordx4 v[164:165], off
	v_lshl_add_u64 v[168:169], s[44:45], 0, v[130:131]
	s_mov_b32 m0, s48
	s_nop 0
	global_load_lds_dwordx4 v[168:169], off
	s_barrier
	s_waitcnt lgkmcnt(0)
	s_waitcnt lgkmcnt(0)
	s_cmp_eq_u32 s64, -2
	s_cbranch_scc1 .Lz10_2_first
	v_mfma_f32_16x16x32_bf16 v[60:63], v[146:149], v[186:189], v[60:63]
	v_mfma_f32_16x16x32_bf16 v[56:59], v[178:181], v[186:189], v[56:59]
	v_mfma_f32_16x16x32_bf16 v[44:47], v[146:149], v[200:203], v[44:47]
	v_mfma_f32_16x16x32_bf16 v[40:43], v[178:181], v[200:203], v[40:43]
	v_mfma_f32_16x16x32_bf16 v[28:31], v[146:149], v[208:211], v[28:31]
	v_mfma_f32_16x16x32_bf16 v[24:27], v[178:181], v[208:211], v[24:27]
	v_mfma_f32_16x16x32_bf16 v[12:15], v[146:149], v[216:219], v[12:15]
	v_mfma_f32_16x16x32_bf16 v[8:11], v[178:181], v[216:219], v[8:11]
	v_mfma_f32_16x16x32_bf16 v[60:63], v[150:153], v[196:199], v[60:63]
	v_mfma_f32_16x16x32_bf16 v[56:59], v[182:185], v[196:199], v[56:59]
	v_mfma_f32_16x16x32_bf16 v[44:47], v[150:153], v[204:207], v[44:47]
	v_mfma_f32_16x16x32_bf16 v[40:43], v[182:185], v[204:207], v[40:43]
	v_mfma_f32_16x16x32_bf16 v[28:31], v[150:153], v[212:215], v[28:31]
	v_mfma_f32_16x16x32_bf16 v[24:27], v[182:185], v[212:215], v[24:27]
	v_mfma_f32_16x16x32_bf16 v[12:15], v[150:153], v[220:223], v[12:15]
	v_mfma_f32_16x16x32_bf16 v[8:11], v[182:185], v[220:223], v[8:11]
.Lz10_2_join:
	s_barrier
	s_add_u32 s66, s42, 0x40000
	s_addc_u32 s67, s43, 0
	s_add_i32 s28, s57, s11
	v_lshl_add_u64 v[146:147], s[66:67], 0, v[132:133]
	s_mov_b32 m0, s28
	s_nop 0
	global_load_lds_dwordx4 v[146:147], off
	v_lshl_add_u64 v[146:147], s[66:67], 0, v[128:129]
	s_add_i32 m0, s28, 0x2000
	s_nop 0
	global_load_lds_dwordx4 v[146:147], off
	s_waitcnt vmcnt(6)
	s_barrier
	s_cmp_eq_u32 s64, -2
	s_cbranch_scc1 .Lz10_3_first
	v_mfma_f32_16x16x32_bf16 v[52:55], v[224:227], v[186:189], v[52:55]
	v_mfma_f32_16x16x32_bf16 v[48:51], v[232:235], v[186:189], v[48:51]
	v_mfma_f32_16x16x32_bf16 v[36:39], v[224:227], v[200:203], v[36:39]
	v_mfma_f32_16x16x32_bf16 v[32:35], v[232:235], v[200:203], v[32:35]
	v_mfma_f32_16x16x32_bf16 v[20:23], v[224:227], v[208:211], v[20:23]
	v_mfma_f32_16x16x32_bf16 v[16:19], v[232:235], v[208:211], v[16:19]
	v_mfma_f32_16x16x32_bf16 v[4:7], v[224:227], v[216:219], v[4:7]
	v_mfma_f32_16x16x32_bf16 v[0:3], v[232:235], v[216:219], v[0:3]
	v_mfma_f32_16x16x32_bf16 v[52:55], v[228:231], v[196:199], v[52:55]
	v_mfma_f32_16x16x32_bf16 v[48:51], v[236:239], v[196:199], v[48:51]
	v_mfma_f32_16x16x32_bf16 v[36:39], v[228:231], v[204:207], v[36:39]
	v_mfma_f32_16x16x32_bf16 v[32:35], v[236:239], v[204:207], v[32:35]
	v_mfma_f32_16x16x32_bf16 v[20:23], v[228:231], v[212:215], v[20:23]
	v_mfma_f32_16x16x32_bf16 v[16:19], v[236:239], v[212:215], v[16:19]
	v_mfma_f32_16x16x32_bf16 v[4:7], v[228:231], v[220:223], v[4:7]
	v_mfma_f32_16x16x32_bf16 v[0:3], v[236:239], v[220:223], v[0:3]
.Lz10_3_join:
	s_add_i32 s28, 0, 0x18000
	v_add_u32_e32 v154, s28, v159
	s_barrier
	ds_read_b128 v[146:149], v154
	ds_read_b128 v[150:153], v154 offset:1024
	ds_read_b128 v[178:181], v154 offset:2048
	ds_read_b128 v[182:185], v154 offset:3072
	s_add_u32 s44, s44, 0x40000
	s_addc_u32 s45, s45, 0
	s_mov_b32 m0, s49
	v_lshl_add_u64 v[172:173], s[44:45], 0, v[134:135]
	ds_read_b128 v[186:189], v171 offset:32768
	ds_read_b128 v[196:199], v171 offset:33792
	ds_read_b128 v[200:203], v171 offset:34816
	ds_read_b128 v[204:207], v171 offset:35840
	ds_read_b128 v[208:211], v171 offset:36864
	ds_read_b128 v[212:215], v171 offset:37888
	ds_read_b128 v[216:219], v171 offset:38912
	ds_read_b128 v[220:223], v171 offset:39936
	global_load_lds_dwordx4 v[172:173], off
	v_lshl_add_u64 v[172:173], s[44:45], 0, v[130:131]
	s_mov_b32 m0, s50
	s_nop 0
	global_load_lds_dwordx4 v[172:173], off
	s_waitcnt lgkmcnt(8)
	s_barrier
	s_waitcnt lgkmcnt(0)
	s_waitcnt lgkmcnt(0)
	v_mfma_f32_16x16x32_bf16 v[124:127], v[146:149], v[186:189], v[124:127]
	v_mfma_f32_16x16x32_bf16 v[120:123], v[178:181], v[186:189], v[120:123]
	v_mfma_f32_16x16x32_bf16 v[108:111], v[146:149], v[200:203], v[108:111]
	v_mfma_f32_16x16x32_bf16 v[104:107], v[178:181], v[200:203], v[104:107]
	v_mfma_f32_16x16x32_bf16 v[92:95], v[146:149], v[208:211], v[92:95]
	v_mfma_f32_16x16x32_bf16 v[88:91], v[178:181], v[208:211], v[88:91]
	v_mfma_f32_16x16x32_bf16 v[76:79], v[146:149], v[216:219], v[76:79]
	v_mfma_f32_16x16x32_bf16 v[72:75], v[178:181], v[216:219], v[72:75]
	v_mfma_f32_16x16x32_bf16 v[124:127], v[150:153], v[196:199], v[124:127]
	v_mfma_f32_16x16x32_bf16 v[120:123], v[182:185], v[196:199], v[120:123]
	v_mfma_f32_16x16x32_bf16 v[108:111], v[150:153], v[204:207], v[108:111]
	v_mfma_f32_16x16x32_bf16 v[104:107], v[182:185], v[204:207], v[104:107]
	v_mfma_f32_16x16x32_bf16 v[92:95], v[150:153], v[212:215], v[92:95]
	v_mfma_f32_16x16x32_bf16 v[88:91], v[182:185], v[212:215], v[88:91]
	v_mfma_f32_16x16x32_bf16 v[76:79], v[150:153], v[220:223], v[76:79]
	v_mfma_f32_16x16x32_bf16 v[72:75], v[182:185], v[220:223], v[72:75]
	s_barrier
	s_add_i32 s29, 0, 0x1c000
	s_add_i32 s28, s28, s11
	v_add_u32_e32 v154, s29, v159
	v_lshl_add_u64 v[156:157], v[156:157], 0, s[6:7]
	s_mov_b32 m0, s28
	ds_read_b128 v[224:227], v154
	ds_read_b128 v[228:231], v154 offset:1024
	ds_read_b128 v[232:235], v154 offset:2048
	ds_read_b128 v[236:239], v154 offset:3072
	global_load_lds_dwordx4 v[156:157], off
	v_lshl_add_u64 v[156:157], v[160:161], 0, s[6:7]
	s_add_i32 m0, s28, 0x2000
	s_nop 0
	global_load_lds_dwordx4 v[156:157], off
	s_barrier
	s_waitcnt lgkmcnt(0)
	s_waitcnt lgkmcnt(0)
	v_mfma_f32_16x16x32_bf16 v[116:119], v[224:227], v[186:189], v[116:119]
	v_mfma_f32_16x16x32_bf16 v[112:115], v[232:235], v[186:189], v[112:115]
	v_mfma_f32_16x16x32_bf16 v[100:103], v[224:227], v[200:203], v[100:103]
	v_mfma_f32_16x16x32_bf16 v[96:99], v[232:235], v[200:203], v[96:99]
	v_mfma_f32_16x16x32_bf16 v[84:87], v[224:227], v[208:211], v[84:87]
	v_mfma_f32_16x16x32_bf16 v[80:83], v[232:235], v[208:211], v[80:83]
	v_mfma_f32_16x16x32_bf16 v[68:71], v[224:227], v[216:219], v[68:71]
	v_mfma_f32_16x16x32_bf16 v[64:67], v[232:235], v[216:219], v[64:67]
	v_mfma_f32_16x16x32_bf16 v[116:119], v[228:231], v[196:199], v[116:119]
	v_mfma_f32_16x16x32_bf16 v[112:115], v[236:239], v[196:199], v[112:115]
	v_mfma_f32_16x16x32_bf16 v[100:103], v[228:231], v[204:207], v[100:103]
	v_mfma_f32_16x16x32_bf16 v[96:99], v[236:239], v[204:207], v[96:99]
	v_mfma_f32_16x16x32_bf16 v[84:87], v[228:231], v[212:215], v[84:87]
	v_mfma_f32_16x16x32_bf16 v[80:83], v[236:239], v[212:215], v[80:83]
	v_mfma_f32_16x16x32_bf16 v[68:71], v[228:231], v[220:223], v[68:71]
	v_mfma_f32_16x16x32_bf16 v[64:67], v[236:239], v[220:223], v[64:67]
	s_mov_b32 m0, s53
	v_lshl_add_u64 v[156:157], v[164:165], 0, s[6:7]
	s_barrier
	ds_read_b128 v[186:189], v171 offset:49152
	ds_read_b128 v[196:199], v171 offset:50176
	ds_read_b128 v[200:203], v171 offset:51200
	ds_read_b128 v[204:207], v171 offset:52224
	ds_read_b128 v[208:211], v171 offset:53248
	ds_read_b128 v[212:215], v171 offset:54272
	ds_read_b128 v[216:219], v171 offset:55296
	ds_read_b128 v[220:223], v171 offset:56320
	global_load_lds_dwordx4 v[156:157], off
	v_lshl_add_u64 v[156:157], v[168:169], 0, s[6:7]
	s_mov_b32 m0, s54
	s_nop 0
	global_load_lds_dwordx4 v[156:157], off
	s_barrier
	s_waitcnt lgkmcnt(0)
	s_waitcnt lgkmcnt(0)
	v_mfma_f32_16x16x32_bf16 v[60:63], v[146:149], v[186:189], v[60:63]
	v_mfma_f32_16x16x32_bf16 v[56:59], v[178:181], v[186:189], v[56:59]
	v_mfma_f32_16x16x32_bf16 v[44:47], v[146:149], v[200:203], v[44:47]
	v_mfma_f32_16x16x32_bf16 v[40:43], v[178:181], v[200:203], v[40:43]
	v_mfma_f32_16x16x32_bf16 v[28:31], v[146:149], v[208:211], v[28:31]
	v_mfma_f32_16x16x32_bf16 v[24:27], v[178:181], v[208:211], v[24:27]
	v_mfma_f32_16x16x32_bf16 v[12:15], v[146:149], v[216:219], v[12:15]
	v_mfma_f32_16x16x32_bf16 v[8:11], v[178:181], v[216:219], v[8:11]
	v_mfma_f32_16x16x32_bf16 v[60:63], v[150:153], v[196:199], v[60:63]
	v_mfma_f32_16x16x32_bf16 v[56:59], v[182:185], v[196:199], v[56:59]
	v_mfma_f32_16x16x32_bf16 v[44:47], v[150:153], v[204:207], v[44:47]
	v_mfma_f32_16x16x32_bf16 v[40:43], v[182:185], v[204:207], v[40:43]
	v_mfma_f32_16x16x32_bf16 v[28:31], v[150:153], v[212:215], v[28:31]
	v_mfma_f32_16x16x32_bf16 v[24:27], v[182:185], v[212:215], v[24:27]
	v_mfma_f32_16x16x32_bf16 v[12:15], v[150:153], v[220:223], v[12:15]
	v_mfma_f32_16x16x32_bf16 v[8:11], v[182:185], v[220:223], v[8:11]
	s_barrier
	s_add_u32 s42, s42, 0x40080
	s_addc_u32 s43, s43, 0
	s_add_i32 s28, s29, s11
	v_lshl_add_u64 v[146:147], s[42:43], 0, v[132:133]
	s_mov_b32 m0, s28
	s_nop 0
	global_load_lds_dwordx4 v[146:147], off
	v_lshl_add_u64 v[146:147], s[42:43], 0, v[128:129]
	s_add_i32 m0, s28, 0x2000
	s_nop 0
	global_load_lds_dwordx4 v[146:147], off
	s_waitcnt vmcnt(6)
	s_barrier
	v_mfma_f32_16x16x32_bf16 v[52:55], v[224:227], v[186:189], v[52:55]
	v_mfma_f32_16x16x32_bf16 v[48:51], v[232:235], v[186:189], v[48:51]
	v_mfma_f32_16x16x32_bf16 v[36:39], v[224:227], v[200:203], v[36:39]
	v_mfma_f32_16x16x32_bf16 v[32:35], v[232:235], v[200:203], v[32:35]
	v_mfma_f32_16x16x32_bf16 v[20:23], v[224:227], v[208:211], v[20:23]
	v_mfma_f32_16x16x32_bf16 v[16:19], v[232:235], v[208:211], v[16:19]
	v_mfma_f32_16x16x32_bf16 v[4:7], v[224:227], v[216:219], v[4:7]
	v_mfma_f32_16x16x32_bf16 v[0:3], v[232:235], v[216:219], v[0:3]
	v_mfma_f32_16x16x32_bf16 v[52:55], v[228:231], v[196:199], v[52:55]
	v_mfma_f32_16x16x32_bf16 v[48:51], v[236:239], v[196:199], v[48:51]
	v_mfma_f32_16x16x32_bf16 v[36:39], v[228:231], v[204:207], v[36:39]
	v_mfma_f32_16x16x32_bf16 v[32:35], v[236:239], v[204:207], v[32:35]
	v_mfma_f32_16x16x32_bf16 v[20:23], v[228:231], v[212:215], v[20:23]
	v_mfma_f32_16x16x32_bf16 v[16:19], v[236:239], v[212:215], v[16:19]
	v_mfma_f32_16x16x32_bf16 v[4:7], v[228:231], v[220:223], v[4:7]
	v_mfma_f32_16x16x32_bf16 v[0:3], v[236:239], v[220:223], v[0:3]
	s_add_i32 s64, s64, 2
	s_add_u32 s0, s0, 0x100
	s_addc_u32 s1, s1, 0
	s_add_u32 s62, s62, 0x100
	s_addc_u32 s63, s63, 0
	s_cmp_gt_u32 s64, 13
	s_barrier
	s_cbranch_scc0 .LBB0_1093
	s_branch .Lz10_skip

.Lz10_skip:
	v_lshl_add_u32 v168, s4, 8, v155
	v_or_b32_e32 v164, 16, v168
	v_or_b32_e32 v160, 32, v168
	v_or_b32_e32 v156, 48, v168
	v_add_u32_e32 v152, 0x80, v168
	v_add_u32_e32 v150, 0x90, v168
	v_add_u32_e32 v148, 0xa0, v168
	v_add_u32_e32 v146, 0xb0, v168
	v_lshl_or_b32 v172, s5, 7, v163
	v_mov_b32_e32 v178, v240
	v_mov_b32_e32 v179, v240
	v_mov_b32_e32 v154, v241
	s_and_b32 s0, s36, 0x7f
	v_lshl_add_u32 v228, s0, 8, v155
	v_mov_b32_e32 v229, 0
	v_lshlrev_b32_e32 v228, 6, v228
	v_lshl_add_u64 v[230:231], v[136:137], 0, v[228:229]
	v_mov_b32_e32 v228, 0x2000
	v_lshl_add_u64 v[232:233], v[230:231], 0, v[228:229]
	global_load_dwordx4 v[216:219], v[230:231], off
	global_load_dwordx4 v[220:223], v[230:231], off offset:1024
	global_load_dwordx4 v[224:227], v[230:231], off offset:2048
	global_load_dwordx4 v[196:199], v[230:231], off offset:3072
	global_load_dwordx4 v[200:203], v[232:233], off
	global_load_dwordx4 v[204:207], v[232:233], off offset:1024
	global_load_dwordx4 v[208:211], v[232:233], off offset:2048
	global_load_dwordx4 v[212:215], v[232:233], off offset:3072
	v_pk_mul_f32 v[124:125], v[124:125], v[178:179] op_sel_hi:[1,0]
	v_pk_mul_f32 v[126:127], v[126:127], v[178:179] op_sel_hi:[1,0]
	v_mul_f32_e32 v147, 0xbfb8aa3b, v124
	v_exp_f32_e32 v147, v147
	v_mul_f32_e32 v149, 0xbfb8aa3b, v125
	v_exp_f32_e32 v149, v149
	v_mul_f32_e32 v151, 0xbfb8aa3b, v127
	v_add_f32_e32 v147, 1.0, v147
	v_rcp_f32_e32 v180, v147
	v_add_f32_e32 v147, 1.0, v149
	v_mul_f32_e32 v149, 0xbfb8aa3b, v126
	v_exp_f32_e32 v149, v149
	v_exp_f32_e32 v151, v151
	v_rcp_f32_e32 v181, v147
	v_pk_mul_f32 v[116:117], v[116:117], v[178:179] op_sel_hi:[1,0]
	v_add_f32_e32 v147, 1.0, v149
	v_rcp_f32_e32 v182, v147
	v_add_f32_e32 v147, 1.0, v151
	v_rcp_f32_e32 v183, v147
	v_pk_mul_f32 v[124:125], v[124:125], v[180:181]
	v_pk_mul_f32 v[120:121], v[120:121], v[178:179] op_sel_hi:[1,0]
	v_pk_mul_f32 v[116:117], v[116:117], v[124:125]
	v_pk_mul_f32 v[124:125], v[126:127], v[182:183]
	v_mul_f32_e32 v126, 0xbfb8aa3b, v120
	v_exp_f32_e32 v126, v126
	v_pk_mul_f32 v[118:119], v[118:119], v[178:179] op_sel_hi:[1,0]
	v_pk_mul_f32 v[122:123], v[122:123], v[178:179] op_sel_hi:[1,0]
	v_pk_mul_f32 v[118:119], v[118:119], v[124:125]
	v_mul_f32_e32 v124, 0xbfb8aa3b, v121
	v_exp_f32_e32 v125, v124
	v_add_f32_e32 v124, 1.0, v126
	v_mul_f32_e32 v126, 0xbfb8aa3b, v122
	v_mul_f32_e32 v127, 0xbfb8aa3b, v123
	v_exp_f32_e32 v126, v126
	v_exp_f32_e32 v127, v127
	v_add_f32_e32 v125, 1.0, v125
	v_rcp_f32_e32 v124, v124
	v_rcp_f32_e32 v125, v125
	v_add_f32_e32 v126, 1.0, v126
	v_add_f32_e32 v127, 1.0, v127
	v_rcp_f32_e32 v126, v126
	v_rcp_f32_e32 v127, v127
	v_pk_mul_f32 v[112:113], v[112:113], v[178:179] op_sel_hi:[1,0]
	v_pk_mul_f32 v[120:121], v[120:121], v[124:125]
	v_pk_mul_f32 v[114:115], v[114:115], v[178:179] op_sel_hi:[1,0]
	v_pk_mul_f32 v[112:113], v[112:113], v[120:121]
	v_pk_mul_f32 v[120:121], v[122:123], v[126:127]
	v_ashrrev_i32_e32 v173, 31, v172
	v_pk_mul_f32 v[114:115], v[114:115], v[120:121]
	v_cvt_pk_bf16_f32 v116, v116, v117
	v_cvt_pk_bf16_f32 v117, v118, v119
	v_cvt_pk_bf16_f32 v118, v112, v113
	v_mov_b64_e32 v[112:113], s[20:21]
	v_cvt_pk_bf16_f32 v119, v114, v115
	v_mad_i64_i32 v[120:121], s[0:1], v168, s59, v[112:113]
	v_lshlrev_b64 v[114:115], 1, v[172:173]
	v_lshl_add_u64 v[120:121], v[120:121], 0, v[114:115]
	v_pk_mul_f32 v[108:109], v[108:109], v[176:177] op_sel_hi:[1,0]
	global_store_dwordx4 v[120:121], v[116:119], off
	v_mul_f32_e32 v122, 0xbfb8aa3b, v108
	v_pk_mul_f32 v[110:111], v[110:111], v[176:177] op_sel_hi:[1,0]
	v_mul_f32_e32 v116, 0xbfb8aa3b, v109
	v_exp_f32_e32 v122, v122
	v_exp_f32_e32 v117, v116
	v_mul_f32_e32 v118, 0xbfb8aa3b, v110
	v_mul_f32_e32 v119, 0xbfb8aa3b, v111
	v_exp_f32_e32 v118, v118
	v_exp_f32_e32 v119, v119
	v_add_f32_e32 v116, 1.0, v122
	v_add_f32_e32 v117, 1.0, v117
	v_rcp_f32_e32 v116, v116
	v_rcp_f32_e32 v117, v117
	v_add_f32_e32 v118, 1.0, v118
	v_add_f32_e32 v119, 1.0, v119
	v_rcp_f32_e32 v118, v118
	v_rcp_f32_e32 v119, v119
	v_pk_mul_f32 v[100:101], v[100:101], v[176:177] op_sel_hi:[1,0]
	v_pk_mul_f32 v[108:109], v[108:109], v[116:117]
	v_pk_mul_f32 v[104:105], v[104:105], v[176:177] op_sel_hi:[1,0]
	v_pk_mul_f32 v[100:101], v[100:101], v[108:109]
	v_pk_mul_f32 v[108:109], v[110:111], v[118:119]
	v_mul_f32_e32 v110, 0xbfb8aa3b, v104
	v_exp_f32_e32 v110, v110
	v_pk_mul_f32 v[102:103], v[102:103], v[176:177] op_sel_hi:[1,0]
	v_pk_mul_f32 v[106:107], v[106:107], v[176:177] op_sel_hi:[1,0]
	v_pk_mul_f32 v[102:103], v[102:103], v[108:109]
	v_mul_f32_e32 v108, 0xbfb8aa3b, v105
	v_exp_f32_e32 v109, v108
	v_add_f32_e32 v108, 1.0, v110
	v_mul_f32_e32 v110, 0xbfb8aa3b, v106
	v_mul_f32_e32 v111, 0xbfb8aa3b, v107
	v_exp_f32_e32 v110, v110
	v_exp_f32_e32 v111, v111
	v_add_f32_e32 v109, 1.0, v109
	v_rcp_f32_e32 v108, v108
	v_rcp_f32_e32 v109, v109
	v_add_f32_e32 v110, 1.0, v110
	v_add_f32_e32 v111, 1.0, v111
	v_rcp_f32_e32 v110, v110
	v_rcp_f32_e32 v111, v111
	v_pk_mul_f32 v[96:97], v[96:97], v[176:177] op_sel_hi:[1,0]
	v_pk_mul_f32 v[104:105], v[104:105], v[108:109]
	v_pk_mul_f32 v[92:93], v[92:93], v[174:175] op_sel_hi:[1,0]
	v_pk_mul_f32 v[104:105], v[96:97], v[104:105]
	v_pk_mul_f32 v[96:97], v[98:99], v[176:177] op_sel_hi:[1,0]
	v_pk_mul_f32 v[98:99], v[106:107], v[110:111]
	v_pk_mul_f32 v[94:95], v[94:95], v[174:175] op_sel_hi:[1,0]
	v_pk_mul_f32 v[106:107], v[96:97], v[98:99]
	v_cvt_pk_bf16_f32 v96, v100, v101
	v_mad_i64_i32 v[100:101], s[0:1], v164, s59, v[112:113]
	v_cvt_pk_bf16_f32 v97, v102, v103
	v_cvt_pk_bf16_f32 v98, v104, v105
	v_cvt_pk_bf16_f32 v99, v106, v107
	v_lshl_add_u64 v[100:101], v[100:101], 0, v[114:115]
	v_mul_f32_e32 v102, 0xbfb8aa3b, v92
	global_store_dwordx4 v[100:101], v[96:99], off
	v_exp_f32_e32 v102, v102
	v_pk_mul_f32 v[84:85], v[84:85], v[174:175] op_sel_hi:[1,0]
	v_mul_f32_e32 v96, 0xbfb8aa3b, v93
	v_exp_f32_e32 v97, v96
	v_mul_f32_e32 v98, 0xbfb8aa3b, v94
	v_mul_f32_e32 v99, 0xbfb8aa3b, v95
	v_exp_f32_e32 v98, v98
	v_exp_f32_e32 v99, v99
	v_add_f32_e32 v96, 1.0, v102
	v_add_f32_e32 v97, 1.0, v97
	v_rcp_f32_e32 v96, v96
	v_rcp_f32_e32 v97, v97
	v_add_f32_e32 v98, 1.0, v98
	v_add_f32_e32 v99, 1.0, v99
	v_rcp_f32_e32 v98, v98
	v_rcp_f32_e32 v99, v99
	v_pk_mul_f32 v[92:93], v[92:93], v[96:97]
	v_pk_mul_f32 v[88:89], v[88:89], v[174:175] op_sel_hi:[1,0]
	v_pk_mul_f32 v[84:85], v[84:85], v[92:93]
	v_pk_mul_f32 v[92:93], v[94:95], v[98:99]
	v_mul_f32_e32 v94, 0xbfb8aa3b, v88
	v_exp_f32_e32 v94, v94
	v_pk_mul_f32 v[86:87], v[86:87], v[174:175] op_sel_hi:[1,0]
	v_pk_mul_f32 v[90:91], v[90:91], v[174:175] op_sel_hi:[1,0]
	v_pk_mul_f32 v[86:87], v[86:87], v[92:93]
	v_mul_f32_e32 v92, 0xbfb8aa3b, v89
	v_exp_f32_e32 v93, v92
	v_add_f32_e32 v92, 1.0, v94
	v_mul_f32_e32 v94, 0xbfb8aa3b, v90
	v_mul_f32_e32 v95, 0xbfb8aa3b, v91
	v_exp_f32_e32 v94, v94
	v_exp_f32_e32 v95, v95
	v_add_f32_e32 v93, 1.0, v93
	v_rcp_f32_e32 v92, v92
	v_rcp_f32_e32 v93, v93
	v_add_f32_e32 v94, 1.0, v94
	v_add_f32_e32 v95, 1.0, v95
	v_rcp_f32_e32 v94, v94
	v_rcp_f32_e32 v95, v95
	v_pk_mul_f32 v[80:81], v[80:81], v[174:175] op_sel_hi:[1,0]
	v_pk_mul_f32 v[88:89], v[88:89], v[92:93]
	v_pk_mul_f32 v[76:77], v[76:77], v[170:171] op_sel_hi:[1,0]
	v_pk_mul_f32 v[88:89], v[80:81], v[88:89]
	v_pk_mul_f32 v[80:81], v[82:83], v[174:175] op_sel_hi:[1,0]
	v_pk_mul_f32 v[82:83], v[90:91], v[94:95]
	v_pk_mul_f32 v[78:79], v[78:79], v[170:171] op_sel_hi:[1,0]
	v_pk_mul_f32 v[90:91], v[80:81], v[82:83]
	v_cvt_pk_bf16_f32 v80, v84, v85
	v_mad_i64_i32 v[84:85], s[0:1], v160, s59, v[112:113]
	v_cvt_pk_bf16_f32 v81, v86, v87
	v_cvt_pk_bf16_f32 v82, v88, v89
	v_cvt_pk_bf16_f32 v83, v90, v91
	v_lshl_add_u64 v[84:85], v[84:85], 0, v[114:115]
	v_mul_f32_e32 v86, 0xbfb8aa3b, v76
	global_store_dwordx4 v[84:85], v[80:83], off
	v_exp_f32_e32 v86, v86
	v_pk_mul_f32 v[68:69], v[68:69], v[170:171] op_sel_hi:[1,0]
	v_mul_f32_e32 v80, 0xbfb8aa3b, v77
	v_exp_f32_e32 v81, v80
	v_mul_f32_e32 v82, 0xbfb8aa3b, v78
	v_mul_f32_e32 v83, 0xbfb8aa3b, v79
	v_exp_f32_e32 v82, v82
	v_exp_f32_e32 v83, v83
	v_add_f32_e32 v80, 1.0, v86
	v_add_f32_e32 v81, 1.0, v81
	v_rcp_f32_e32 v80, v80
	v_rcp_f32_e32 v81, v81
	v_add_f32_e32 v82, 1.0, v82
	v_add_f32_e32 v83, 1.0, v83
	v_rcp_f32_e32 v82, v82
	v_rcp_f32_e32 v83, v83
	v_pk_mul_f32 v[76:77], v[76:77], v[80:81]
	v_pk_mul_f32 v[72:73], v[72:73], v[170:171] op_sel_hi:[1,0]
	v_pk_mul_f32 v[68:69], v[68:69], v[76:77]
	v_pk_mul_f32 v[76:77], v[78:79], v[82:83]
	v_mul_f32_e32 v78, 0xbfb8aa3b, v72
	v_exp_f32_e32 v78, v78
	v_pk_mul_f32 v[70:71], v[70:71], v[170:171] op_sel_hi:[1,0]
	v_pk_mul_f32 v[74:75], v[74:75], v[170:171] op_sel_hi:[1,0]
	v_pk_mul_f32 v[70:71], v[70:71], v[76:77]
	v_mul_f32_e32 v76, 0xbfb8aa3b, v73
	v_exp_f32_e32 v77, v76
	v_add_f32_e32 v76, 1.0, v78
	v_mul_f32_e32 v78, 0xbfb8aa3b, v74
	v_mul_f32_e32 v79, 0xbfb8aa3b, v75
	v_exp_f32_e32 v78, v78
	v_exp_f32_e32 v79, v79
	v_add_f32_e32 v77, 1.0, v77
	v_rcp_f32_e32 v76, v76
	v_rcp_f32_e32 v77, v77
	v_add_f32_e32 v78, 1.0, v78
	v_add_f32_e32 v79, 1.0, v79
	v_rcp_f32_e32 v78, v78
	v_rcp_f32_e32 v79, v79
	v_pk_mul_f32 v[64:65], v[64:65], v[170:171] op_sel_hi:[1,0]
	v_pk_mul_f32 v[72:73], v[72:73], v[76:77]
	v_pk_mul_f32 v[60:61], v[60:61], v[166:167] op_sel_hi:[1,0]
	v_pk_mul_f32 v[72:73], v[64:65], v[72:73]
	v_pk_mul_f32 v[64:65], v[66:67], v[170:171] op_sel_hi:[1,0]
	v_pk_mul_f32 v[66:67], v[74:75], v[78:79]
	v_pk_mul_f32 v[62:63], v[62:63], v[166:167] op_sel_hi:[1,0]
	v_pk_mul_f32 v[74:75], v[64:65], v[66:67]
	v_cvt_pk_bf16_f32 v64, v68, v69
	v_mad_i64_i32 v[68:69], s[0:1], v156, s59, v[112:113]
	v_cvt_pk_bf16_f32 v65, v70, v71
	v_cvt_pk_bf16_f32 v66, v72, v73
	v_cvt_pk_bf16_f32 v67, v74, v75
	v_lshl_add_u64 v[68:69], v[68:69], 0, v[114:115]
	v_mul_f32_e32 v70, 0xbfb8aa3b, v60
	global_store_dwordx4 v[68:69], v[64:67], off
	v_exp_f32_e32 v70, v70
	v_pk_mul_f32 v[52:53], v[52:53], v[166:167] op_sel_hi:[1,0]
	v_mul_f32_e32 v64, 0xbfb8aa3b, v61
	v_exp_f32_e32 v65, v64
	v_mul_f32_e32 v66, 0xbfb8aa3b, v62
	v_mul_f32_e32 v67, 0xbfb8aa3b, v63
	v_exp_f32_e32 v66, v66
	v_exp_f32_e32 v67, v67
	v_add_f32_e32 v64, 1.0, v70
	v_add_f32_e32 v65, 1.0, v65
	v_rcp_f32_e32 v64, v64
	v_rcp_f32_e32 v65, v65
	v_add_f32_e32 v66, 1.0, v66
	v_add_f32_e32 v67, 1.0, v67
	v_rcp_f32_e32 v66, v66
	v_rcp_f32_e32 v67, v67
	v_pk_mul_f32 v[60:61], v[60:61], v[64:65]
	v_pk_mul_f32 v[56:57], v[56:57], v[166:167] op_sel_hi:[1,0]
	v_pk_mul_f32 v[52:53], v[52:53], v[60:61]
	v_pk_mul_f32 v[60:61], v[62:63], v[66:67]
	v_mul_f32_e32 v62, 0xbfb8aa3b, v56
	v_exp_f32_e32 v62, v62
	v_pk_mul_f32 v[54:55], v[54:55], v[166:167] op_sel_hi:[1,0]
	v_pk_mul_f32 v[58:59], v[58:59], v[166:167] op_sel_hi:[1,0]
	v_pk_mul_f32 v[54:55], v[54:55], v[60:61]
	v_mul_f32_e32 v60, 0xbfb8aa3b, v57
	v_exp_f32_e32 v61, v60
	v_add_f32_e32 v60, 1.0, v62
	v_mul_f32_e32 v62, 0xbfb8aa3b, v58
	v_mul_f32_e32 v63, 0xbfb8aa3b, v59
	v_exp_f32_e32 v62, v62
	v_exp_f32_e32 v63, v63
	v_add_f32_e32 v61, 1.0, v61
	v_rcp_f32_e32 v60, v60
	v_rcp_f32_e32 v61, v61
	v_add_f32_e32 v62, 1.0, v62
	v_add_f32_e32 v63, 1.0, v63
	v_rcp_f32_e32 v62, v62
	v_rcp_f32_e32 v63, v63
	v_pk_mul_f32 v[48:49], v[48:49], v[166:167] op_sel_hi:[1,0]
	v_pk_mul_f32 v[56:57], v[56:57], v[60:61]
	v_pk_mul_f32 v[44:45], v[44:45], v[162:163] op_sel_hi:[1,0]
	v_pk_mul_f32 v[56:57], v[48:49], v[56:57]
	v_pk_mul_f32 v[48:49], v[50:51], v[166:167] op_sel_hi:[1,0]
	v_pk_mul_f32 v[50:51], v[58:59], v[62:63]
	v_pk_mul_f32 v[46:47], v[46:47], v[162:163] op_sel_hi:[1,0]
	v_pk_mul_f32 v[58:59], v[48:49], v[50:51]
	v_cvt_pk_bf16_f32 v48, v52, v53
	v_mad_i64_i32 v[52:53], s[0:1], v152, s59, v[112:113]
	v_cvt_pk_bf16_f32 v49, v54, v55
	v_cvt_pk_bf16_f32 v50, v56, v57
	v_cvt_pk_bf16_f32 v51, v58, v59
	v_lshl_add_u64 v[52:53], v[52:53], 0, v[114:115]
	v_mul_f32_e32 v54, 0xbfb8aa3b, v44
	global_store_dwordx4 v[52:53], v[48:51], off
	v_exp_f32_e32 v54, v54
	v_pk_mul_f32 v[36:37], v[36:37], v[162:163] op_sel_hi:[1,0]
	v_mul_f32_e32 v48, 0xbfb8aa3b, v45
	v_exp_f32_e32 v49, v48
	v_mul_f32_e32 v50, 0xbfb8aa3b, v46
	v_mul_f32_e32 v51, 0xbfb8aa3b, v47
	v_exp_f32_e32 v50, v50
	v_exp_f32_e32 v51, v51
	v_add_f32_e32 v48, 1.0, v54
	v_add_f32_e32 v49, 1.0, v49
	v_rcp_f32_e32 v48, v48
	v_rcp_f32_e32 v49, v49
	v_add_f32_e32 v50, 1.0, v50
	v_add_f32_e32 v51, 1.0, v51
	v_rcp_f32_e32 v50, v50
	v_rcp_f32_e32 v51, v51
	v_pk_mul_f32 v[44:45], v[44:45], v[48:49]
	v_pk_mul_f32 v[40:41], v[40:41], v[162:163] op_sel_hi:[1,0]
	v_pk_mul_f32 v[36:37], v[36:37], v[44:45]
	v_pk_mul_f32 v[44:45], v[46:47], v[50:51]
	v_mul_f32_e32 v46, 0xbfb8aa3b, v40
	v_exp_f32_e32 v46, v46
	v_pk_mul_f32 v[38:39], v[38:39], v[162:163] op_sel_hi:[1,0]
	v_pk_mul_f32 v[42:43], v[42:43], v[162:163] op_sel_hi:[1,0]
	v_pk_mul_f32 v[38:39], v[38:39], v[44:45]
	v_mul_f32_e32 v44, 0xbfb8aa3b, v41
	v_exp_f32_e32 v45, v44
	v_add_f32_e32 v44, 1.0, v46
	v_mul_f32_e32 v46, 0xbfb8aa3b, v42
	v_mul_f32_e32 v47, 0xbfb8aa3b, v43
	v_exp_f32_e32 v46, v46
	v_exp_f32_e32 v47, v47
	v_add_f32_e32 v45, 1.0, v45
	v_rcp_f32_e32 v44, v44
	v_rcp_f32_e32 v45, v45
	v_add_f32_e32 v46, 1.0, v46
	v_add_f32_e32 v47, 1.0, v47
	v_rcp_f32_e32 v46, v46
	v_rcp_f32_e32 v47, v47
	v_pk_mul_f32 v[32:33], v[32:33], v[162:163] op_sel_hi:[1,0]
	v_pk_mul_f32 v[40:41], v[40:41], v[44:45]
	v_pk_mul_f32 v[28:29], v[28:29], v[158:159] op_sel_hi:[1,0]
	v_pk_mul_f32 v[40:41], v[32:33], v[40:41]
	v_pk_mul_f32 v[32:33], v[34:35], v[162:163] op_sel_hi:[1,0]
	v_pk_mul_f32 v[34:35], v[42:43], v[46:47]
	v_pk_mul_f32 v[30:31], v[30:31], v[158:159] op_sel_hi:[1,0]
	v_pk_mul_f32 v[42:43], v[32:33], v[34:35]
	v_cvt_pk_bf16_f32 v32, v36, v37
	v_mad_i64_i32 v[36:37], s[0:1], v150, s59, v[112:113]
	v_cvt_pk_bf16_f32 v33, v38, v39
	v_cvt_pk_bf16_f32 v34, v40, v41
	v_cvt_pk_bf16_f32 v35, v42, v43
	v_lshl_add_u64 v[36:37], v[36:37], 0, v[114:115]
	v_mul_f32_e32 v38, 0xbfb8aa3b, v28
	global_store_dwordx4 v[36:37], v[32:35], off
	v_exp_f32_e32 v38, v38
	v_pk_mul_f32 v[20:21], v[20:21], v[158:159] op_sel_hi:[1,0]
	v_mul_f32_e32 v32, 0xbfb8aa3b, v29
	v_exp_f32_e32 v33, v32
	v_mul_f32_e32 v34, 0xbfb8aa3b, v30
	v_mul_f32_e32 v35, 0xbfb8aa3b, v31
	v_exp_f32_e32 v34, v34
	v_exp_f32_e32 v35, v35
	v_add_f32_e32 v32, 1.0, v38
	v_add_f32_e32 v33, 1.0, v33
	v_rcp_f32_e32 v32, v32
	v_rcp_f32_e32 v33, v33
	v_add_f32_e32 v34, 1.0, v34
	v_add_f32_e32 v35, 1.0, v35
	v_rcp_f32_e32 v34, v34
	v_rcp_f32_e32 v35, v35
	v_pk_mul_f32 v[28:29], v[28:29], v[32:33]
	v_pk_mul_f32 v[24:25], v[24:25], v[158:159] op_sel_hi:[1,0]
	v_pk_mul_f32 v[20:21], v[20:21], v[28:29]
	v_pk_mul_f32 v[28:29], v[30:31], v[34:35]
	v_mul_f32_e32 v30, 0xbfb8aa3b, v24
	v_exp_f32_e32 v30, v30
	v_pk_mul_f32 v[22:23], v[22:23], v[158:159] op_sel_hi:[1,0]
	v_pk_mul_f32 v[26:27], v[26:27], v[158:159] op_sel_hi:[1,0]
	v_pk_mul_f32 v[22:23], v[22:23], v[28:29]
	v_mul_f32_e32 v28, 0xbfb8aa3b, v25
	v_exp_f32_e32 v29, v28
	v_add_f32_e32 v28, 1.0, v30
	v_mul_f32_e32 v30, 0xbfb8aa3b, v26
	v_mul_f32_e32 v31, 0xbfb8aa3b, v27
	v_exp_f32_e32 v30, v30
	v_exp_f32_e32 v31, v31
	v_add_f32_e32 v29, 1.0, v29
	v_rcp_f32_e32 v28, v28
	v_rcp_f32_e32 v29, v29
	v_add_f32_e32 v30, 1.0, v30
	v_add_f32_e32 v31, 1.0, v31
	v_rcp_f32_e32 v30, v30
	v_rcp_f32_e32 v31, v31
	v_pk_mul_f32 v[16:17], v[16:17], v[158:159] op_sel_hi:[1,0]
	v_pk_mul_f32 v[24:25], v[24:25], v[28:29]
	v_pk_mul_f32 v[12:13], v[12:13], v[154:155] op_sel_hi:[1,0]
	v_pk_mul_f32 v[24:25], v[16:17], v[24:25]
	v_pk_mul_f32 v[16:17], v[18:19], v[158:159] op_sel_hi:[1,0]
	v_pk_mul_f32 v[18:19], v[26:27], v[30:31]
	v_pk_mul_f32 v[14:15], v[14:15], v[154:155] op_sel_hi:[1,0]
	v_pk_mul_f32 v[26:27], v[16:17], v[18:19]
	v_cvt_pk_bf16_f32 v16, v20, v21
	v_mad_i64_i32 v[20:21], s[0:1], v148, s59, v[112:113]
	v_cvt_pk_bf16_f32 v17, v22, v23
	v_cvt_pk_bf16_f32 v18, v24, v25
	v_cvt_pk_bf16_f32 v19, v26, v27
	v_lshl_add_u64 v[20:21], v[20:21], 0, v[114:115]
	v_mul_f32_e32 v22, 0xbfb8aa3b, v12
	global_store_dwordx4 v[20:21], v[16:19], off
	v_exp_f32_e32 v22, v22
	v_pk_mul_f32 v[4:5], v[4:5], v[154:155] op_sel_hi:[1,0]
	v_mul_f32_e32 v16, 0xbfb8aa3b, v13
	v_exp_f32_e32 v17, v16
	v_mul_f32_e32 v18, 0xbfb8aa3b, v14
	v_mul_f32_e32 v19, 0xbfb8aa3b, v15
	v_exp_f32_e32 v18, v18
	v_exp_f32_e32 v19, v19
	v_add_f32_e32 v16, 1.0, v22
	v_add_f32_e32 v17, 1.0, v17
	v_rcp_f32_e32 v16, v16
	v_rcp_f32_e32 v17, v17
	v_add_f32_e32 v18, 1.0, v18
	v_add_f32_e32 v19, 1.0, v19
	v_rcp_f32_e32 v18, v18
	v_rcp_f32_e32 v19, v19
	v_pk_mul_f32 v[12:13], v[12:13], v[16:17]
	v_pk_mul_f32 v[8:9], v[8:9], v[154:155] op_sel_hi:[1,0]
	v_pk_mul_f32 v[4:5], v[4:5], v[12:13]
	v_pk_mul_f32 v[12:13], v[14:15], v[18:19]
	v_mul_f32_e32 v14, 0xbfb8aa3b, v8
	v_exp_f32_e32 v14, v14
	v_pk_mul_f32 v[6:7], v[6:7], v[154:155] op_sel_hi:[1,0]
	v_pk_mul_f32 v[10:11], v[10:11], v[154:155] op_sel_hi:[1,0]
	v_pk_mul_f32 v[6:7], v[6:7], v[12:13]
	v_mul_f32_e32 v12, 0xbfb8aa3b, v9
	v_exp_f32_e32 v13, v12
	v_add_f32_e32 v12, 1.0, v14
	v_mul_f32_e32 v14, 0xbfb8aa3b, v10
	v_mul_f32_e32 v15, 0xbfb8aa3b, v11
	v_exp_f32_e32 v14, v14
	v_exp_f32_e32 v15, v15
	v_add_f32_e32 v13, 1.0, v13
	v_rcp_f32_e32 v12, v12
	v_rcp_f32_e32 v13, v13
	v_add_f32_e32 v14, 1.0, v14
	v_add_f32_e32 v15, 1.0, v15
	v_rcp_f32_e32 v14, v14
	v_rcp_f32_e32 v15, v15
	v_pk_mul_f32 v[0:1], v[0:1], v[154:155] op_sel_hi:[1,0]
	v_pk_mul_f32 v[8:9], v[8:9], v[12:13]
	s_and_b64 vcc, exec, s[2:3]
	v_pk_mul_f32 v[8:9], v[0:1], v[8:9]
	v_pk_mul_f32 v[0:1], v[2:3], v[154:155] op_sel_hi:[1,0]
	v_pk_mul_f32 v[2:3], v[10:11], v[14:15]
	s_mov_b32 s5, s12
	v_pk_mul_f32 v[10:11], v[0:1], v[2:3]
	v_cvt_pk_bf16_f32 v0, v4, v5
	v_mad_i64_i32 v[4:5], s[0:1], v146, s59, v[112:113]
	v_cvt_pk_bf16_f32 v1, v6, v7
	v_cvt_pk_bf16_f32 v2, v8, v9
	v_cvt_pk_bf16_f32 v3, v10, v11
	v_lshl_add_u64 v[4:5], v[4:5], 0, v[114:115]
	s_mov_b32 s4, s36
	s_mov_b64 s[42:43], s[40:41]
	s_mov_b64 s[44:45], s[38:39]
	global_store_dwordx4 v[4:5], v[0:3], off
	s_waitcnt vmcnt(8)
	v_xor_b32_e32 v184, 16, v177
	v_xor_b32_e32 v185, 32, v177
	v_lshlrev_b32_e32 v184, 2, v184
	v_lshlrev_b32_e32 v185, 2, v185
	v_mov_b32_e32 v190, s10
	v_pk_add_f32 v[216:217], v[216:217], v[218:219]
	v_pk_add_f32 v[220:221], v[220:221], v[222:223]
	v_pk_add_f32 v[224:225], v[224:225], v[226:227]
	v_pk_add_f32 v[196:197], v[196:197], v[198:199]
	v_pk_add_f32 v[200:201], v[200:201], v[202:203]
	v_pk_add_f32 v[204:205], v[204:205], v[206:207]
	v_pk_add_f32 v[208:209], v[208:209], v[210:211]
	v_pk_add_f32 v[212:213], v[212:213], v[214:215]
	v_add_f32_e32 v216, v216, v217
	v_add_f32_e32 v220, v220, v221
	v_add_f32_e32 v224, v224, v225
	v_add_f32_e32 v196, v196, v197
	v_add_f32_e32 v200, v200, v201
	v_add_f32_e32 v204, v204, v205
	v_add_f32_e32 v208, v208, v209
	v_add_f32_e32 v212, v212, v213
	ds_bpermute_b32 v218, v184, v216
	ds_bpermute_b32 v219, v184, v220
	ds_bpermute_b32 v222, v184, v224
	ds_bpermute_b32 v223, v184, v196
	ds_bpermute_b32 v226, v184, v200
	ds_bpermute_b32 v227, v184, v204
	ds_bpermute_b32 v198, v184, v208
	ds_bpermute_b32 v199, v184, v212
	s_waitcnt lgkmcnt(0)
	v_add_f32_e32 v216, v216, v218
	v_add_f32_e32 v220, v220, v219
	v_add_f32_e32 v224, v224, v222
	v_add_f32_e32 v196, v196, v223
	v_add_f32_e32 v200, v200, v226
	v_add_f32_e32 v204, v204, v227
	v_add_f32_e32 v208, v208, v198
	v_add_f32_e32 v212, v212, v199
	ds_bpermute_b32 v218, v185, v216
	ds_bpermute_b32 v219, v185, v220
	ds_bpermute_b32 v222, v185, v224
	ds_bpermute_b32 v223, v185, v196
	ds_bpermute_b32 v226, v185, v200
	ds_bpermute_b32 v227, v185, v204
	ds_bpermute_b32 v198, v185, v208
	ds_bpermute_b32 v199, v185, v212
	s_waitcnt lgkmcnt(0)
	v_add_f32_e32 v216, v216, v218
	v_add_f32_e32 v220, v220, v219
	v_add_f32_e32 v224, v224, v222
	v_add_f32_e32 v196, v196, v223
	v_add_f32_e32 v200, v200, v226
	v_add_f32_e32 v204, v204, v227
	v_add_f32_e32 v208, v208, v198
	v_add_f32_e32 v212, v212, v199
	v_fma_f32 v216, v216, s8, v190
	v_fma_f32 v220, v220, s8, v190
	v_fma_f32 v224, v224, s8, v190
	v_fma_f32 v196, v196, s8, v190
	v_fma_f32 v200, v200, s8, v190
	v_fma_f32 v204, v204, s8, v190
	v_fma_f32 v208, v208, s8, v190
	v_fma_f32 v212, v212, s8, v190
	v_rsq_f32_e32 v240, v216
	v_rsq_f32_e32 v176, v220
	v_rsq_f32_e32 v174, v224
	v_rsq_f32_e32 v170, v196
	v_rsq_f32_e32 v166, v200
	v_rsq_f32_e32 v162, v204
	v_rsq_f32_e32 v158, v208
	v_rsq_f32_e32 v241, v212
	s_and_b64 vcc, exec, s[2:3]
	s_mov_b32 s5, s12
	s_mov_b32 s4, s36
	s_cbranch_vccz .LBB0_1090
	s_setprio 0
	s_waitcnt vmcnt(0)
	s_cmpk_gt_u32 s9, 0xff
	s_cbranch_scc1 .LBB0_1097
	s_barrier
